# fp8 operands in conflict-free LDS layout + first K-iteration peeled with SrcC=0 (no accumulator zeroing) in the int8 up/down and bf16 loops
# speedup vs baseline: 1.0171x; 1.0068x over previous
;     __device__ __forceinline__ bool next(int i, Unit& u) const { const int off = i * H + (r >> 1); if (off >= 8 * nN) return false; u.pm = 16 * g + 8 * (r & 1) + (off & 7); u.pn = off >> 3; return true; }
; #define PG8_STAGE(bufoff, gbase, unused) do { _Pragma("unroll") for (int _i = 0; _i < 2; ++_i) \
;         __builtin_amdgcn_global_load_lds((const unsigned*)((const char*)(gbase) + voff + _i * 8192), (LAS unsigned*)(lds + (bufoff) + ldsw + _i * 8192), 16, 0, 0); } while (0)
; #define PG8_LDA(dst, b, h) do { _Pragma("unroll") for (int m = 0; m < 4; ++m) _Pragma("unroll") for (int k = 0; k < 2; ++k) dst[m][k] = *(const LAS bf16x8*)(lds + PG8_SA(b, h) + aoff + m * 2048 + (FP8 ? k * 16 : k * 1024)); } while (0)
; #define PG8_LDB(dst, b, h) do { _Pragma("unroll") for (int n = 0; n < 2; ++n) _Pragma("unroll") for (int k = 0; k < 2; ++k) dst[n][k] = *(const LAS bf16x8*)(lds + PG8_SB(b, h) + boff + n * 2048 + (FP8 ? k * 16 : k * 1024)); } while (0)
; template <class Epi, class Sched, bool ALIGN_EPI, bool SP2, int MODE  >
; __device__ __forceinline__ void gemm_phase(LAS unsigned char* lds, const Gemm g, const Sched S, const Epi E, unsigned long long& probe_acc, int epi_id, int wv) {
;     ...
;     for (;;) {
;         const bool has_next = S.next(ui + 1, nxt);
;         const char* nA = has_next ? (const char*)g.A + (size_t)nxt.pm * tA + (g.gt ? (size_t)(nxt.pn / g.gt) * gK2 : 0) : cA; const char* nB = has_next ? (const char*)g.Bt + (size_t)nxt.pn * tB : cB;
;         for (int t = 0; t < nt; t += 2) {
;             const bool last = (t == nt - 2);
;             const char* a1 = cA + (size_t)(t + 1) * kstep;
;             const char* a2 = last ? nA : cA + (size_t)(t + 2) * kstep; const char* b2 = last ? nB : cB + (size_t)(t + 2) * kstep;
;             const char* a3 = a2 + kstep; const char* b3 = b2 + kstep;
;             if constexpr (SP2) {
;             PG8_LDB(B0, 0, 0); PG8_LDB(B1, 0, 1); PG8_SCHED; PG8_LDA(At, 0, 0); PG8_STAGE(PG8_SA(1, 1), a1 + hA, voffA);
;             PG8_WAIT_V(8); PG8_WAIT_L(0); PG8_BAR; PG8_MMA(0, 0, At, B0); PG8_MMA(0, 1, At, B1); PG8_BAR; PG8_SCHED;
;             PG8_LDA(At, 0, 1); PG8_STAGE(PG8_SB(0, 0), b2, voffB); PG8_STAGE(PG8_SB(0, 1), b2 + hB, voffB); PG8_STAGE(PG8_SA(0, 0), a2, voffA);
;             PG8_WAIT_V(8); PG8_WAIT_L(0); PG8_BAR; PG8_MMA(1, 0, At, B0); PG8_MMA(1, 1, At, B1); PG8_BAR; PG8_SCHED;
.LBB0_325:
	s_mov_b64 s[28:29], s[10:11]
	s_mov_b32 s11, s1
	s_mov_b32 s26, s1
	s_add_i32 s40, s40, 1
	v_readlane_b32 s1, v254, 6
	s_mov_b64 s[14:15], s[4:5]
	s_mul_i32 s1, s40, s1
	v_readlane_b32 s4, v254, 35
	s_add_i32 s1, s1, s4
	s_cmpk_lt_i32 s1, 0x160
	s_cselect_b64 s[24:25], -1, 0
	s_and_b32 s4, s1, 7
	v_readlane_b32 s5, v254, 18
	s_mov_b32 s10, s69
	s_mov_b32 s8, s69
	s_or_b32 s69, s4, s5
	s_ashr_i32 s1, s1, 3
	s_and_b64 s[4:5], s[24:25], exec
	s_cselect_b32 s10, s69, s10
	s_cselect_b32 s4, s1, s11
	s_ashr_i32 s11, s10, 31
	s_lshl_b64 s[10:11], s[10:11], 19
	s_add_u32 s10, s34, s10
	s_addc_u32 s11, s35, s11
	s_and_b64 s[16:17], s[24:25], exec
	s_cselect_b32 s27, s11, s29
	s_cselect_b32 s46, s10, s28
	s_ashr_i32 s5, s4, 31
	s_lshl_b64 s[4:5], s[4:5], 19
	s_add_u32 s4, s36, s4
	s_addc_u32 s5, s37, s5
	s_and_b64 s[16:17], s[24:25], exec
	s_cselect_b32 vcc_lo, s5, s15
	s_cselect_b32 vcc_hi, s4, s14
	s_add_u32 s16, s14, 0x8000
	s_addc_u32 s17, s15, 0
	s_mov_b32 s14, -2
	s_waitcnt lgkmcnt(0)
	v_add_u32_e32 v0, s39, v212
	ds_read_b128 v[132:135], v0
	ds_read_b128 v[136:139], v0 offset:1024
	ds_read_b128 v[140:143], v0 offset:2048
	ds_read_b128 v[144:147], v0 offset:3072
	v_add_u32_e32 v0, s65, v212
	ds_read_b128 v[148:151], v0
	ds_read_b128 v[152:155], v0 offset:1024
	ds_read_b128 v[156:159], v0 offset:2048
	ds_read_b128 v[160:163], v0 offset:3072
	s_add_u32 s30, s28, 0x8000
	s_addc_u32 s31, s29, 0
	s_cmp_eq_u32 s14, 12
	s_cselect_b32 s23, s27, s31
	s_cselect_b32 s22, s46, s30
	s_cselect_b32 s21, vcc_lo, s17
	s_cselect_b32 s20, vcc_hi, s16
	v_lshl_add_u64 v[184:185], s[28:29], 0, v[130:131]
	v_lshl_add_u64 v[204:205], v[184:185], 0, s[80:81]
	s_add_i32 m0, s85, 0xc000
	ds_read_b128 v[164:167], v213
	ds_read_b128 v[168:171], v213 offset:1024
	ds_read_b128 v[172:175], v213 offset:2048
	ds_read_b128 v[176:179], v213 offset:3072
	ds_read_b128 v[180:183], v213 offset:4096
	ds_read_b128 v[190:193], v213 offset:5120
	ds_read_b128 v[196:199], v213 offset:6144
	ds_read_b128 v[200:203], v213 offset:7168
	global_load_lds_dwordx4 v[204:205], off
	v_lshl_add_u64 v[184:185], v[184:185], 0, s[82:83]
	s_add_i32 m0, s85, 0xe000
	s_nop 0
	global_load_lds_dwordx4 v[184:185], off
	s_waitcnt vmcnt(8)
	s_waitcnt lgkmcnt(0)
	s_barrier
	s_setprio 1
	s_waitcnt lgkmcnt(0)
	v_mfma_i32_16x16x64_i8 v[126:129], v[132:135], v[164:167], 0
	v_mfma_i32_16x16x64_i8 v[102:105], v[140:143], v[164:167], 0
	v_mfma_i32_16x16x64_i8 v[122:125], v[132:135], v[172:175], 0
	v_mfma_i32_16x16x64_i8 v[94:97], v[140:143], v[172:175], 0
	v_mfma_i32_16x16x64_i8 v[118:121], v[132:135], v[180:183], 0
	v_mfma_i32_16x16x64_i8 v[46:49], v[140:143], v[180:183], 0
	v_mfma_i32_16x16x64_i8 v[110:113], v[132:135], v[196:199], 0
	v_mfma_i32_16x16x64_i8 v[38:41], v[140:143], v[196:199], 0
	v_mfma_i32_16x16x64_i8 v[126:129], v[136:139], v[168:171], v[126:129]
	v_mfma_i32_16x16x64_i8 v[102:105], v[144:147], v[168:171], v[102:105]
	v_mfma_i32_16x16x64_i8 v[122:125], v[136:139], v[176:179], v[122:125]
	v_mfma_i32_16x16x64_i8 v[94:97], v[144:147], v[176:179], v[94:97]
	v_mfma_i32_16x16x64_i8 v[118:121], v[136:139], v[190:193], v[118:121]
	v_mfma_i32_16x16x64_i8 v[46:49], v[144:147], v[190:193], v[46:49]
	v_mfma_i32_16x16x64_i8 v[110:113], v[136:139], v[200:203], v[110:113]
	v_mfma_i32_16x16x64_i8 v[38:41], v[144:147], v[200:203], v[38:41]
	s_setprio 0
	s_setprio 1
	v_mfma_i32_16x16x64_i8 v[114:117], v[148:151], v[164:167], 0
	v_mfma_i32_16x16x64_i8 v[82:85], v[156:159], v[164:167], 0
	v_mfma_i32_16x16x64_i8 v[106:109], v[148:151], v[172:175], 0
	v_mfma_i32_16x16x64_i8 v[74:77], v[156:159], v[172:175], 0
	v_mfma_i32_16x16x64_i8 v[98:101], v[148:151], v[180:183], 0
	v_mfma_i32_16x16x64_i8 v[42:45], v[156:159], v[180:183], 0
	v_mfma_i32_16x16x64_i8 v[90:93], v[148:151], v[196:199], 0
	v_mfma_i32_16x16x64_i8 v[34:37], v[156:159], v[196:199], 0
	v_mfma_i32_16x16x64_i8 v[114:117], v[152:155], v[168:171], v[114:117]
	v_mfma_i32_16x16x64_i8 v[82:85], v[160:163], v[168:171], v[82:85]
	v_mfma_i32_16x16x64_i8 v[106:109], v[152:155], v[176:179], v[106:109]
	v_mfma_i32_16x16x64_i8 v[74:77], v[160:163], v[176:179], v[74:77]
	v_mfma_i32_16x16x64_i8 v[98:101], v[152:155], v[190:193], v[98:101]
	v_mfma_i32_16x16x64_i8 v[42:45], v[160:163], v[190:193], v[42:45]
	v_mfma_i32_16x16x64_i8 v[90:93], v[152:155], v[200:203], v[90:93]
	v_mfma_i32_16x16x64_i8 v[34:37], v[160:163], v[200:203], v[34:37]
	s_setprio 0
	s_barrier
	s_mov_b32 m0, s41
	v_lshl_add_u64 v[184:185], s[20:21], 0, v[130:131]
	ds_read_b128 v[164:167], v213 offset:16384
	ds_read_b128 v[168:171], v213 offset:17408
	ds_read_b128 v[172:175], v213 offset:18432
	ds_read_b128 v[176:179], v213 offset:19456
	ds_read_b128 v[180:183], v213 offset:20480
	ds_read_b128 v[190:193], v213 offset:21504
	ds_read_b128 v[196:199], v213 offset:22528
	ds_read_b128 v[200:203], v213 offset:23552
	global_load_lds_dwordx4 v[184:185], off
	v_lshl_add_u64 v[204:205], v[184:185], 0, s[70:71]
	s_mov_b32 m0, s64
	s_nop 0
	global_load_lds_dwordx4 v[204:205], off
	v_lshl_add_u64 v[204:205], v[184:185], 0, s[72:73]
	s_mov_b32 m0, s68
	s_nop 0
	global_load_lds_dwordx4 v[204:205], off
	v_lshl_add_u64 v[204:205], v[184:185], 0, s[74:75]
	s_mov_b32 m0, s84
	s_nop 0
	global_load_lds_dwordx4 v[204:205], off
	v_lshl_add_u64 v[204:205], s[22:23], 0, v[130:131]
	s_mov_b32 m0, s85
	v_lshl_add_u64 v[206:207], v[204:205], 0, s[70:71]
	global_load_lds_dwordx4 v[204:205], off
	s_mov_b32 m0, s86
	s_nop 0
	global_load_lds_dwordx4 v[206:207], off
	s_waitcnt vmcnt(8)
	s_waitcnt lgkmcnt(0)
	s_barrier
; #define PG8_STAGE(bufoff, gbase, unused) do { _Pragma("unroll") for (int _i = 0; _i < 2; ++_i) \
;         __builtin_amdgcn_global_load_lds((const unsigned*)((const char*)(gbase) + voff + _i * 8192), (LAS unsigned*)(lds + (bufoff) + ldsw + _i * 8192), 16, 0, 0); } while (0)
; #define PG8_LDA(dst, b, h) do { _Pragma("unroll") for (int m = 0; m < 4; ++m) _Pragma("unroll") for (int k = 0; k < 2; ++k) dst[m][k] = *(const LAS bf16x8*)(lds + PG8_SA(b, h) + aoff + m * 2048 + (FP8 ? k * 16 : k * 1024)); } while (0)
; #define PG8_LDB(dst, b, h) do { _Pragma("unroll") for (int n = 0; n < 2; ++n) _Pragma("unroll") for (int k = 0; k < 2; ++k) dst[n][k] = *(const LAS bf16x8*)(lds + PG8_SB(b, h) + boff + n * 2048 + (FP8 ? k * 16 : k * 1024)); } while (0)
; #define PG8_WAIT_V(n) asm volatile("s_waitcnt vmcnt(" #n ")" ::: "memory")
; #define PG8_WAIT_L(n) asm volatile("s_waitcnt lgkmcnt(" #n ")" ::: "memory")
; #define PG8_BAR __builtin_amdgcn_s_barrier()
; #define PG8_SCHED __builtin_amdgcn_sched_barrier(0)
; template <class Epi, class Sched, bool ALIGN_EPI, bool SP2, int MODE  >
; __device__ __forceinline__ void gemm_phase(LAS unsigned char* lds, const Gemm g, const Sched S, const Epi E, unsigned long long& probe_acc, int epi_id, int wv) {
;     ...
;             PG8_WAIT_V(8); PG8_WAIT_L(0); PG8_BAR; PG8_MMA(1, 0, At, B0); PG8_MMA(1, 1, At, B1); PG8_BAR; PG8_SCHED;
;             PG8_LDB(B0, 1, 0); PG8_LDB(B1, 1, 1); PG8_SCHED; PG8_LDA(At, 1, 0); PG8_STAGE(PG8_SA(0, 1), a2 + hA, voffA);
;             PG8_WAIT_V(8); PG8_WAIT_L(0); PG8_BAR; PG8_MMA(0, 0, At, B0); PG8_MMA(0, 1, At, B1); PG8_BAR; PG8_SCHED;
;             PG8_LDA(At, 1, 1); PG8_STAGE(PG8_SB(1, 0), b3, voffB); PG8_STAGE(PG8_SB(1, 1), b3 + hB, voffB); PG8_STAGE(PG8_SA(1, 0), a3, voffA);
	s_setprio 1
	s_waitcnt lgkmcnt(0)
	v_mfma_i32_16x16x64_i8 v[86:89], v[132:135], v[164:167], 0
	v_mfma_i32_16x16x64_i8 v[30:33], v[140:143], v[164:167], 0
	v_mfma_i32_16x16x64_i8 v[78:81], v[132:135], v[172:175], 0
	v_mfma_i32_16x16x64_i8 v[22:25], v[140:143], v[172:175], 0
	v_mfma_i32_16x16x64_i8 v[70:73], v[132:135], v[180:183], 0
	v_mfma_i32_16x16x64_i8 v[14:17], v[140:143], v[180:183], 0
	v_mfma_i32_16x16x64_i8 v[62:65], v[132:135], v[196:199], 0
	v_mfma_i32_16x16x64_i8 v[2:5], v[140:143], v[196:199], 0
	v_mfma_i32_16x16x64_i8 v[86:89], v[136:139], v[168:171], v[86:89]
	v_mfma_i32_16x16x64_i8 v[30:33], v[144:147], v[168:171], v[30:33]
	v_mfma_i32_16x16x64_i8 v[78:81], v[136:139], v[176:179], v[78:81]
	v_mfma_i32_16x16x64_i8 v[22:25], v[144:147], v[176:179], v[22:25]
	v_mfma_i32_16x16x64_i8 v[70:73], v[136:139], v[190:193], v[70:73]
	v_mfma_i32_16x16x64_i8 v[14:17], v[144:147], v[190:193], v[14:17]
	v_mfma_i32_16x16x64_i8 v[62:65], v[136:139], v[200:203], v[62:65]
	v_mfma_i32_16x16x64_i8 v[2:5], v[144:147], v[200:203], v[2:5]
	s_setprio 0
	s_setprio 1
	v_mfma_i32_16x16x64_i8 v[66:69], v[148:151], v[164:167], 0
	v_mfma_i32_16x16x64_i8 v[26:29], v[156:159], v[164:167], 0
	v_mfma_i32_16x16x64_i8 v[58:61], v[148:151], v[172:175], 0
	v_mfma_i32_16x16x64_i8 v[18:21], v[156:159], v[172:175], 0
	v_mfma_i32_16x16x64_i8 v[54:57], v[148:151], v[180:183], 0
	v_mfma_i32_16x16x64_i8 v[10:13], v[156:159], v[180:183], 0
	v_mfma_i32_16x16x64_i8 v[50:53], v[148:151], v[196:199], 0
	v_mfma_i32_16x16x64_i8 v[6:9], v[156:159], v[196:199], 0
	v_mfma_i32_16x16x64_i8 v[66:69], v[152:155], v[168:171], v[66:69]
	v_mfma_i32_16x16x64_i8 v[26:29], v[160:163], v[168:171], v[26:29]
	v_mfma_i32_16x16x64_i8 v[58:61], v[152:155], v[176:179], v[58:61]
	v_mfma_i32_16x16x64_i8 v[18:21], v[160:163], v[176:179], v[18:21]
	v_mfma_i32_16x16x64_i8 v[54:57], v[152:155], v[190:193], v[54:57]
	v_mfma_i32_16x16x64_i8 v[10:13], v[160:163], v[190:193], v[10:13]
	v_mfma_i32_16x16x64_i8 v[50:53], v[152:155], v[200:203], v[50:53]
	v_mfma_i32_16x16x64_i8 v[6:9], v[160:163], v[200:203], v[6:9]
	s_setprio 0
	s_barrier
	v_add_u32_e32 v0, s90, v212
	ds_read_b128 v[132:135], v0
	ds_read_b128 v[136:139], v0 offset:1024
	ds_read_b128 v[140:143], v0 offset:2048
	ds_read_b128 v[144:147], v0 offset:3072
	v_add_u32_e32 v0, s95, v212
	ds_read_b128 v[148:151], v0
	ds_read_b128 v[152:155], v0 offset:1024
	ds_read_b128 v[156:159], v0 offset:2048
	ds_read_b128 v[160:163], v0 offset:3072
	s_mov_b32 m0, s87
	v_lshl_add_u64 v[206:207], v[204:205], 0, s[72:73]
	ds_read_b128 v[164:167], v213 offset:32768
	ds_read_b128 v[168:171], v213 offset:33792
	ds_read_b128 v[172:175], v213 offset:34816
	ds_read_b128 v[176:179], v213 offset:35840
	ds_read_b128 v[180:183], v213 offset:36864
	ds_read_b128 v[190:193], v213 offset:37888
	ds_read_b128 v[196:199], v213 offset:38912
	ds_read_b128 v[200:203], v213 offset:39936
	global_load_lds_dwordx4 v[206:207], off
	v_lshl_add_u64 v[206:207], v[204:205], 0, s[74:75]
	s_mov_b32 m0, s88
	s_nop 0
	global_load_lds_dwordx4 v[206:207], off
	s_waitcnt vmcnt(8)
	s_waitcnt lgkmcnt(0)
	s_barrier
	s_setprio 1
	s_waitcnt lgkmcnt(0)
	v_mfma_i32_16x16x64_i8 v[126:129], v[132:135], v[164:167], v[126:129]
	v_mfma_i32_16x16x64_i8 v[102:105], v[140:143], v[164:167], v[102:105]
	v_mfma_i32_16x16x64_i8 v[122:125], v[132:135], v[172:175], v[122:125]
	v_mfma_i32_16x16x64_i8 v[94:97], v[140:143], v[172:175], v[94:97]
	v_mfma_i32_16x16x64_i8 v[118:121], v[132:135], v[180:183], v[118:121]
	v_mfma_i32_16x16x64_i8 v[46:49], v[140:143], v[180:183], v[46:49]
	v_mfma_i32_16x16x64_i8 v[110:113], v[132:135], v[196:199], v[110:113]
	v_mfma_i32_16x16x64_i8 v[38:41], v[140:143], v[196:199], v[38:41]
	v_mfma_i32_16x16x64_i8 v[126:129], v[136:139], v[168:171], v[126:129]
	v_mfma_i32_16x16x64_i8 v[102:105], v[144:147], v[168:171], v[102:105]
	v_mfma_i32_16x16x64_i8 v[122:125], v[136:139], v[176:179], v[122:125]
	v_mfma_i32_16x16x64_i8 v[94:97], v[144:147], v[176:179], v[94:97]
	v_mfma_i32_16x16x64_i8 v[118:121], v[136:139], v[190:193], v[118:121]
	v_mfma_i32_16x16x64_i8 v[46:49], v[144:147], v[190:193], v[46:49]
	v_mfma_i32_16x16x64_i8 v[110:113], v[136:139], v[200:203], v[110:113]
	v_mfma_i32_16x16x64_i8 v[38:41], v[144:147], v[200:203], v[38:41]
	s_setprio 0
	s_setprio 1
	v_mfma_i32_16x16x64_i8 v[114:117], v[148:151], v[164:167], v[114:117]
	v_mfma_i32_16x16x64_i8 v[82:85], v[156:159], v[164:167], v[82:85]
	v_mfma_i32_16x16x64_i8 v[106:109], v[148:151], v[172:175], v[106:109]
	v_mfma_i32_16x16x64_i8 v[74:77], v[156:159], v[172:175], v[74:77]
	v_mfma_i32_16x16x64_i8 v[98:101], v[148:151], v[180:183], v[98:101]
	v_mfma_i32_16x16x64_i8 v[42:45], v[156:159], v[180:183], v[42:45]
	v_mfma_i32_16x16x64_i8 v[90:93], v[148:151], v[196:199], v[90:93]
	v_mfma_i32_16x16x64_i8 v[34:37], v[156:159], v[196:199], v[34:37]
	v_mfma_i32_16x16x64_i8 v[114:117], v[152:155], v[168:171], v[114:117]
	v_mfma_i32_16x16x64_i8 v[82:85], v[160:163], v[168:171], v[82:85]
	v_mfma_i32_16x16x64_i8 v[106:109], v[152:155], v[176:179], v[106:109]
	v_mfma_i32_16x16x64_i8 v[74:77], v[160:163], v[176:179], v[74:77]
	v_mfma_i32_16x16x64_i8 v[98:101], v[152:155], v[190:193], v[98:101]
	v_mfma_i32_16x16x64_i8 v[42:45], v[160:163], v[190:193], v[42:45]
	v_mfma_i32_16x16x64_i8 v[90:93], v[152:155], v[200:203], v[90:93]
	v_mfma_i32_16x16x64_i8 v[34:37], v[160:163], v[200:203], v[34:37]
	s_setprio 0
	s_barrier
; #define PG8_STAGE(bufoff, gbase, unused) do { _Pragma("unroll") for (int _i = 0; _i < 2; ++_i) \
;         __builtin_amdgcn_global_load_lds((const unsigned*)((const char*)(gbase) + voff + _i * 8192), (LAS unsigned*)(lds + (bufoff) + ldsw + _i * 8192), 16, 0, 0); } while (0)
; #define PG8_LDA(dst, b, h) do { _Pragma("unroll") for (int m = 0; m < 4; ++m) _Pragma("unroll") for (int k = 0; k < 2; ++k) dst[m][k] = *(const LAS bf16x8*)(lds + PG8_SA(b, h) + aoff + m * 2048 + (FP8 ? k * 16 : k * 1024)); } while (0)
; #define PG8_WAIT_V(n) asm volatile("s_waitcnt vmcnt(" #n ")" ::: "memory")
; #define PG8_WAIT_L(n) asm volatile("s_waitcnt lgkmcnt(" #n ")" ::: "memory")
; #define PG8_BAR __builtin_amdgcn_s_barrier()
; #define PG8_SCHED __builtin_amdgcn_sched_barrier(0)
; template <class Epi, class Sched, bool ALIGN_EPI, bool SP2, int MODE  >
; __device__ __forceinline__ void gemm_phase(LAS unsigned char* lds, const Gemm g, const Sched S, const Epi E, unsigned long long& probe_acc, int epi_id, int wv) {
;     ...
;             PG8_LDA(At, 1, 1); PG8_STAGE(PG8_SB(1, 0), b3, voffB); PG8_STAGE(PG8_SB(1, 1), b3 + hB, voffB); PG8_STAGE(PG8_SA(1, 0), a3, voffA);
;             PG8_WAIT_V(8); PG8_WAIT_L(0); PG8_BAR; PG8_MMA(1, 0, At, B0); PG8_MMA(1, 1, At, B1); PG8_BAR; PG8_SCHED;
	s_mov_b32 m0, s91
	v_lshl_add_u64 v[206:207], v[184:185], 0, s[76:77]
	ds_read_b128 v[164:167], v213 offset:49152
	ds_read_b128 v[168:171], v213 offset:50176
	ds_read_b128 v[172:175], v213 offset:51200
	ds_read_b128 v[176:179], v213 offset:52224
	ds_read_b128 v[180:183], v213 offset:53248
	ds_read_b128 v[190:193], v213 offset:54272
	ds_read_b128 v[196:199], v213 offset:55296
	ds_read_b128 v[200:203], v213 offset:56320
	global_load_lds_dwordx4 v[206:207], off
	v_lshl_add_u64 v[206:207], v[184:185], 0, s[78:79]
	s_mov_b32 m0, s92
	s_nop 0
	global_load_lds_dwordx4 v[206:207], off
	v_lshl_add_u64 v[206:207], v[184:185], 0, s[80:81]
	s_mov_b32 m0, s2
	v_lshl_add_u64 v[184:185], v[184:185], 0, s[82:83]
	global_load_lds_dwordx4 v[206:207], off
	s_mov_b32 m0, s3
	s_nop 0
	global_load_lds_dwordx4 v[184:185], off
	v_lshl_add_u64 v[184:185], v[204:205], 0, s[76:77]
	s_mov_b32 m0, s93
	s_nop 0
	global_load_lds_dwordx4 v[184:185], off
	v_lshl_add_u64 v[184:185], v[204:205], 0, s[78:79]
	s_mov_b32 m0, s94
	s_nop 0
	global_load_lds_dwordx4 v[184:185], off
	s_waitcnt vmcnt(8)
	s_waitcnt lgkmcnt(0)
	s_barrier
	s_setprio 1
	s_waitcnt lgkmcnt(0)
	v_mfma_i32_16x16x64_i8 v[86:89], v[132:135], v[164:167], v[86:89]
	v_mfma_i32_16x16x64_i8 v[30:33], v[140:143], v[164:167], v[30:33]
	v_mfma_i32_16x16x64_i8 v[78:81], v[132:135], v[172:175], v[78:81]
	v_mfma_i32_16x16x64_i8 v[22:25], v[140:143], v[172:175], v[22:25]
	v_mfma_i32_16x16x64_i8 v[70:73], v[132:135], v[180:183], v[70:73]
	v_mfma_i32_16x16x64_i8 v[14:17], v[140:143], v[180:183], v[14:17]
	v_mfma_i32_16x16x64_i8 v[62:65], v[132:135], v[196:199], v[62:65]
	v_mfma_i32_16x16x64_i8 v[2:5], v[140:143], v[196:199], v[2:5]
	v_mfma_i32_16x16x64_i8 v[86:89], v[136:139], v[168:171], v[86:89]
	v_mfma_i32_16x16x64_i8 v[30:33], v[144:147], v[168:171], v[30:33]
	v_mfma_i32_16x16x64_i8 v[78:81], v[136:139], v[176:179], v[78:81]
	v_mfma_i32_16x16x64_i8 v[22:25], v[144:147], v[176:179], v[22:25]
	v_mfma_i32_16x16x64_i8 v[70:73], v[136:139], v[190:193], v[70:73]
	v_mfma_i32_16x16x64_i8 v[14:17], v[144:147], v[190:193], v[14:17]
	v_mfma_i32_16x16x64_i8 v[62:65], v[136:139], v[200:203], v[62:65]
	v_mfma_i32_16x16x64_i8 v[2:5], v[144:147], v[200:203], v[2:5]
	s_setprio 0
	s_setprio 1
	v_mfma_i32_16x16x64_i8 v[66:69], v[148:151], v[164:167], v[66:69]
	v_mfma_i32_16x16x64_i8 v[26:29], v[156:159], v[164:167], v[26:29]
	v_mfma_i32_16x16x64_i8 v[58:61], v[148:151], v[172:175], v[58:61]
	v_mfma_i32_16x16x64_i8 v[18:21], v[156:159], v[172:175], v[18:21]
	v_mfma_i32_16x16x64_i8 v[54:57], v[148:151], v[180:183], v[54:57]
	v_mfma_i32_16x16x64_i8 v[10:13], v[156:159], v[180:183], v[10:13]
	v_mfma_i32_16x16x64_i8 v[50:53], v[148:151], v[196:199], v[50:53]
	v_mfma_i32_16x16x64_i8 v[6:9], v[156:159], v[196:199], v[6:9]
	v_mfma_i32_16x16x64_i8 v[66:69], v[152:155], v[168:171], v[66:69]
	v_mfma_i32_16x16x64_i8 v[26:29], v[160:163], v[168:171], v[26:29]
	v_mfma_i32_16x16x64_i8 v[58:61], v[152:155], v[176:179], v[58:61]
	v_mfma_i32_16x16x64_i8 v[18:21], v[160:163], v[176:179], v[18:21]
	v_mfma_i32_16x16x64_i8 v[54:57], v[152:155], v[190:193], v[54:57]
	v_mfma_i32_16x16x64_i8 v[10:13], v[160:163], v[190:193], v[10:13]
	v_mfma_i32_16x16x64_i8 v[50:53], v[152:155], v[200:203], v[50:53]
	v_mfma_i32_16x16x64_i8 v[6:9], v[160:163], v[200:203], v[6:9]
	s_setprio 0
	s_barrier
	s_add_i32 s14, s14, 2
	s_add_u32 s16, s16, 0x8000
	s_addc_u32 s17, s17, 0
	s_cmp_gt_u32 s14, 13
	s_mov_b64 s[28:29], s[30:31]

;     __device__ __forceinline__ bool next(int i, Unit& u) const { const int off = i * H + (r >> 1); if (off >= 8 * nN) return false; u.pm = 16 * g + 8 * (r & 1) + (off & 7); u.pn = off >> 3; return true; }
; #define PG8_STAGE(bufoff, gbase, unused) do { _Pragma("unroll") for (int _i = 0; _i < 2; ++_i) \
;         __builtin_amdgcn_global_load_lds((const unsigned*)((const char*)(gbase) + voff + _i * 8192), (LAS unsigned*)(lds + (bufoff) + ldsw + _i * 8192), 16, 0, 0); } while (0)
; #define PG8_LDA(dst, b, h) do { _Pragma("unroll") for (int m = 0; m < 4; ++m) _Pragma("unroll") for (int k = 0; k < 2; ++k) dst[m][k] = *(const LAS bf16x8*)(lds + PG8_SA(b, h) + aoff + m * 2048 + (FP8 ? k * 16 : k * 1024)); } while (0)
; #define PG8_LDB(dst, b, h) do { _Pragma("unroll") for (int n = 0; n < 2; ++n) _Pragma("unroll") for (int k = 0; k < 2; ++k) dst[n][k] = *(const LAS bf16x8*)(lds + PG8_SB(b, h) + boff + n * 2048 + (FP8 ? k * 16 : k * 1024)); } while (0)
; template <class Epi, class Sched, bool ALIGN_EPI, bool SP2, int MODE  >
; __device__ __forceinline__ void gemm_phase(LAS unsigned char* lds, const Gemm g, const Sched S, const Epi E, unsigned long long& probe_acc, int epi_id, int wv) {
;     ...
;     for (;;) {
;         const bool has_next = S.next(ui + 1, nxt);
;         const char* nA = has_next ? (const char*)g.A + (size_t)nxt.pm * tA + (g.gt ? (size_t)(nxt.pn / g.gt) * gK2 : 0) : cA; const char* nB = has_next ? (const char*)g.Bt + (size_t)nxt.pn * tB : cB;
;         for (int t = 0; t < nt; t += 2) {
;             const bool last = (t == nt - 2);
;             const char* a1 = cA + (size_t)(t + 1) * kstep;
;             const char* a2 = last ? nA : cA + (size_t)(t + 2) * kstep; const char* b2 = last ? nB : cB + (size_t)(t + 2) * kstep;
;             const char* a3 = a2 + kstep; const char* b3 = b2 + kstep;
;             if constexpr (SP2) {
;             PG8_LDB(B0, 0, 0); PG8_LDB(B1, 0, 1); PG8_SCHED; PG8_LDA(At, 0, 0); PG8_STAGE(PG8_SA(1, 1), a1 + hA, voffA);
;             PG8_WAIT_V(8); PG8_WAIT_L(0); PG8_BAR; PG8_MMA(0, 0, At, B0); PG8_MMA(0, 1, At, B1); PG8_BAR; PG8_SCHED;
;             PG8_LDA(At, 0, 1); PG8_STAGE(PG8_SB(0, 0), b2, voffB); PG8_STAGE(PG8_SB(0, 1), b2 + hB, voffB); PG8_STAGE(PG8_SA(0, 0), a2, voffA);
;             PG8_WAIT_V(8); PG8_WAIT_L(0); PG8_BAR; PG8_MMA(1, 0, At, B0); PG8_MMA(1, 1, At, B1); PG8_BAR; PG8_SCHED;
.LBB0_364:
	s_mov_b64 s[20:21], s[4:5]
	s_add_i32 s84, s84, 1
	v_readlane_b32 s4, v254, 6
	s_mul_i32 s4, s84, s4
	v_readlane_b32 s5, v254, 35
	s_add_i32 s4, s4, s5
	s_cmpk_lt_i32 s4, 0xc0
	s_mov_b64 s[18:19], s[10:11]
	s_cselect_b64 s[16:17], -1, 0
	s_and_b32 s5, s4, 7
	v_readlane_b32 s10, v254, 18
	s_mov_b32 s8, s87
	s_mov_b32 s9, s86
	s_mov_b32 s88, s87
	s_mov_b32 s89, s86
	s_or_b32 s87, s5, s10
	s_ashr_i32 s86, s4, 3
	s_and_b64 s[4:5], s[16:17], exec
	s_cselect_b32 s10, s87, s8
	s_cselect_b32 s4, s86, s9
	s_ashr_i32 s11, s10, 31
	s_lshl_b64 s[10:11], s[10:11], 20
	s_add_u32 s10, s58, s10
	s_addc_u32 s11, s59, s11
	s_and_b64 s[90:91], s[16:17], exec
	s_cselect_b32 s46, s11, s19
	s_cselect_b32 s90, s10, s18
	s_ashr_i32 s5, s4, 31
	s_lshl_b64 s[4:5], s[4:5], 20
	s_add_u32 s4, s0, s4
	s_addc_u32 s5, s1, s5
	s_and_b64 s[92:93], s[16:17], exec
	s_cselect_b32 s91, s5, s21
	s_cselect_b32 s92, s4, s20
	s_add_u32 s93, s20, 0x8000
	s_addc_u32 s94, s21, 0
	s_mov_b32 s95, -2
	v_add_u32_e32 v0, s2, v166
	s_waitcnt vmcnt(0)
	ds_read_b128 v[130:133], v0
	ds_read_b128 v[134:137], v0 offset:1024
	ds_read_b128 v[138:141], v0 offset:2048
	ds_read_b128 v[142:145], v0 offset:3072
	v_add_u32_e32 v0, s23, v166
	ds_read_b128 v[146:149], v0
	ds_read_b128 v[150:153], v0 offset:1024
	s_waitcnt lgkmcnt(0)
	ds_read_b128 v[156:159], v0 offset:2048
	ds_read_b128 v[160:163], v0 offset:3072
	s_add_u32 s20, s18, 0x8000
	s_addc_u32 s21, s19, 0
	s_cmp_eq_u32 s95, 28
	s_cselect_b32 vcc_hi, s46, s21
	s_cselect_b32 vcc_lo, s90, s20
	s_cselect_b32 s9, s91, s94
	s_cselect_b32 s8, s92, s93
	v_lshl_add_u64 v[184:185], s[18:19], 0, v[154:155]
	v_lshl_add_u64 v[204:205], v[184:185], 0, s[52:53]
	s_add_i32 m0, s26, 0xc000
	ds_read_b128 v[168:171], v167
	ds_read_b128 v[172:175], v167 offset:1024
	ds_read_b128 v[176:179], v167 offset:2048
	ds_read_b128 v[180:183], v167 offset:3072
	ds_read_b128 v[188:191], v167 offset:4096
	ds_read_b128 v[192:195], v167 offset:5120
	ds_read_b128 v[196:199], v167 offset:6144
	ds_read_b128 v[200:203], v167 offset:7168
	global_load_lds_dwordx4 v[204:205], off
	v_lshl_add_u64 v[184:185], v[184:185], 0, s[54:55]
	s_add_i32 m0, s26, 0xe000
	s_nop 0
	global_load_lds_dwordx4 v[184:185], off
	s_waitcnt vmcnt(8)
	s_waitcnt lgkmcnt(0)
	s_barrier
	s_setprio 1
	s_waitcnt lgkmcnt(0)
	v_mfma_f32_16x16x32_bf16 v[126:129], v[130:133], v[168:171], 0
	v_mfma_f32_16x16x32_bf16 v[122:125], v[138:141], v[168:171], 0
	v_mfma_f32_16x16x32_bf16 v[110:113], v[130:133], v[176:179], 0
	v_mfma_f32_16x16x32_bf16 v[106:109], v[138:141], v[176:179], 0
	v_mfma_f32_16x16x32_bf16 v[94:97], v[130:133], v[188:191], 0
	v_mfma_f32_16x16x32_bf16 v[90:93], v[138:141], v[188:191], 0
	v_mfma_f32_16x16x32_bf16 v[78:81], v[130:133], v[196:199], 0
	v_mfma_f32_16x16x32_bf16 v[74:77], v[138:141], v[196:199], 0
	v_mfma_f32_16x16x32_bf16 v[126:129], v[134:137], v[172:175], v[126:129]
	v_mfma_f32_16x16x32_bf16 v[122:125], v[142:145], v[172:175], v[122:125]
	v_mfma_f32_16x16x32_bf16 v[110:113], v[134:137], v[180:183], v[110:113]
	v_mfma_f32_16x16x32_bf16 v[106:109], v[142:145], v[180:183], v[106:109]
	v_mfma_f32_16x16x32_bf16 v[94:97], v[134:137], v[192:195], v[94:97]
	v_mfma_f32_16x16x32_bf16 v[90:93], v[142:145], v[192:195], v[90:93]
	v_mfma_f32_16x16x32_bf16 v[78:81], v[134:137], v[200:203], v[78:81]
	v_mfma_f32_16x16x32_bf16 v[74:77], v[142:145], v[200:203], v[74:77]
	s_setprio 0
	s_setprio 1
	v_mfma_f32_16x16x32_bf16 v[118:121], v[146:149], v[168:171], 0
	v_mfma_f32_16x16x32_bf16 v[114:117], v[156:159], v[168:171], 0
	v_mfma_f32_16x16x32_bf16 v[102:105], v[146:149], v[176:179], 0
	v_mfma_f32_16x16x32_bf16 v[98:101], v[156:159], v[176:179], 0
	v_mfma_f32_16x16x32_bf16 v[86:89], v[146:149], v[188:191], 0
	v_mfma_f32_16x16x32_bf16 v[82:85], v[156:159], v[188:191], 0
	v_mfma_f32_16x16x32_bf16 v[70:73], v[146:149], v[196:199], 0
	v_mfma_f32_16x16x32_bf16 v[66:69], v[156:159], v[196:199], 0
	v_mfma_f32_16x16x32_bf16 v[118:121], v[150:153], v[172:175], v[118:121]
	v_mfma_f32_16x16x32_bf16 v[114:117], v[160:163], v[172:175], v[114:117]
	v_mfma_f32_16x16x32_bf16 v[102:105], v[150:153], v[180:183], v[102:105]
	v_mfma_f32_16x16x32_bf16 v[98:101], v[160:163], v[180:183], v[98:101]
	v_mfma_f32_16x16x32_bf16 v[86:89], v[150:153], v[192:195], v[86:89]
	v_mfma_f32_16x16x32_bf16 v[82:85], v[160:163], v[192:195], v[82:85]
	v_mfma_f32_16x16x32_bf16 v[70:73], v[150:153], v[200:203], v[70:73]
	v_mfma_f32_16x16x32_bf16 v[66:69], v[160:163], v[200:203], v[66:69]
	s_setprio 0
	s_barrier
	s_mov_b32 m0, s3
	v_lshl_add_u64 v[184:185], s[8:9], 0, v[154:155]
	ds_read_b128 v[168:171], v167 offset:16384
	ds_read_b128 v[172:175], v167 offset:17408
	ds_read_b128 v[176:179], v167 offset:18432
	ds_read_b128 v[180:183], v167 offset:19456
	ds_read_b128 v[188:191], v167 offset:20480
	ds_read_b128 v[192:195], v167 offset:21504
	ds_read_b128 v[196:199], v167 offset:22528
	ds_read_b128 v[200:203], v167 offset:23552
	global_load_lds_dwordx4 v[184:185], off
	v_lshl_add_u64 v[204:205], v[184:185], 0, s[70:71]
	s_mov_b32 m0, s22
	s_nop 0
	global_load_lds_dwordx4 v[204:205], off
	v_lshl_add_u64 v[204:205], v[184:185], 0, s[96:97]
	s_mov_b32 m0, s24
	s_nop 0
	global_load_lds_dwordx4 v[204:205], off
	v_lshl_add_u64 v[204:205], v[184:185], 0, s[60:61]
	s_mov_b32 m0, s25
	s_nop 0
	global_load_lds_dwordx4 v[204:205], off
	v_lshl_add_u64 v[204:205], vcc, 0, v[154:155]
	s_mov_b32 m0, s26
	v_lshl_add_u64 v[206:207], v[204:205], 0, s[70:71]
	global_load_lds_dwordx4 v[204:205], off
	s_mov_b32 m0, s27
	s_nop 0
	global_load_lds_dwordx4 v[206:207], off
	s_waitcnt vmcnt(8)
	s_waitcnt lgkmcnt(0)
	s_barrier
; #define PG8_STAGE(bufoff, gbase, unused) do { _Pragma("unroll") for (int _i = 0; _i < 2; ++_i) \
;         __builtin_amdgcn_global_load_lds((const unsigned*)((const char*)(gbase) + voff + _i * 8192), (LAS unsigned*)(lds + (bufoff) + ldsw + _i * 8192), 16, 0, 0); } while (0)
; #define PG8_LDA(dst, b, h) do { _Pragma("unroll") for (int m = 0; m < 4; ++m) _Pragma("unroll") for (int k = 0; k < 2; ++k) dst[m][k] = *(const LAS bf16x8*)(lds + PG8_SA(b, h) + aoff + m * 2048 + (FP8 ? k * 16 : k * 1024)); } while (0)
; #define PG8_LDB(dst, b, h) do { _Pragma("unroll") for (int n = 0; n < 2; ++n) _Pragma("unroll") for (int k = 0; k < 2; ++k) dst[n][k] = *(const LAS bf16x8*)(lds + PG8_SB(b, h) + boff + n * 2048 + (FP8 ? k * 16 : k * 1024)); } while (0)
; #define PG8_WAIT_V(n) asm volatile("s_waitcnt vmcnt(" #n ")" ::: "memory")
; #define PG8_WAIT_L(n) asm volatile("s_waitcnt lgkmcnt(" #n ")" ::: "memory")
; #define PG8_BAR __builtin_amdgcn_s_barrier()
; #define PG8_SCHED __builtin_amdgcn_sched_barrier(0)
; template <class Epi, class Sched, bool ALIGN_EPI, bool SP2, int MODE  >
; __device__ __forceinline__ void gemm_phase(LAS unsigned char* lds, const Gemm g, const Sched S, const Epi E, unsigned long long& probe_acc, int epi_id, int wv) {
;     ...
;             PG8_WAIT_V(8); PG8_WAIT_L(0); PG8_BAR; PG8_MMA(1, 0, At, B0); PG8_MMA(1, 1, At, B1); PG8_BAR; PG8_SCHED;
;             PG8_LDB(B0, 1, 0); PG8_LDB(B1, 1, 1); PG8_SCHED; PG8_LDA(At, 1, 0); PG8_STAGE(PG8_SA(0, 1), a2 + hA, voffA);
;             PG8_WAIT_V(8); PG8_WAIT_L(0); PG8_BAR; PG8_MMA(0, 0, At, B0); PG8_MMA(0, 1, At, B1); PG8_BAR; PG8_SCHED;
;             PG8_LDA(At, 1, 1); PG8_STAGE(PG8_SB(1, 0), b3, voffB); PG8_STAGE(PG8_SB(1, 1), b3 + hB, voffB); PG8_STAGE(PG8_SA(1, 0), a3, voffA);
	s_setprio 1
	s_waitcnt lgkmcnt(0)
	v_mfma_f32_16x16x32_bf16 v[62:65], v[130:133], v[168:171], 0
	v_mfma_f32_16x16x32_bf16 v[58:61], v[138:141], v[168:171], 0
	v_mfma_f32_16x16x32_bf16 v[46:49], v[130:133], v[176:179], 0
	v_mfma_f32_16x16x32_bf16 v[42:45], v[138:141], v[176:179], 0
	v_mfma_f32_16x16x32_bf16 v[30:33], v[130:133], v[188:191], 0
	v_mfma_f32_16x16x32_bf16 v[26:29], v[138:141], v[188:191], 0
	v_mfma_f32_16x16x32_bf16 v[14:17], v[130:133], v[196:199], 0
	v_mfma_f32_16x16x32_bf16 v[10:13], v[138:141], v[196:199], 0
	v_mfma_f32_16x16x32_bf16 v[62:65], v[134:137], v[172:175], v[62:65]
	v_mfma_f32_16x16x32_bf16 v[58:61], v[142:145], v[172:175], v[58:61]
	v_mfma_f32_16x16x32_bf16 v[46:49], v[134:137], v[180:183], v[46:49]
	v_mfma_f32_16x16x32_bf16 v[42:45], v[142:145], v[180:183], v[42:45]
	v_mfma_f32_16x16x32_bf16 v[30:33], v[134:137], v[192:195], v[30:33]
	v_mfma_f32_16x16x32_bf16 v[26:29], v[142:145], v[192:195], v[26:29]
	v_mfma_f32_16x16x32_bf16 v[14:17], v[134:137], v[200:203], v[14:17]
	v_mfma_f32_16x16x32_bf16 v[10:13], v[142:145], v[200:203], v[10:13]
	s_setprio 0
	s_setprio 1
	v_mfma_f32_16x16x32_bf16 v[54:57], v[146:149], v[168:171], 0
	v_mfma_f32_16x16x32_bf16 v[50:53], v[156:159], v[168:171], 0
	v_mfma_f32_16x16x32_bf16 v[38:41], v[146:149], v[176:179], 0
	v_mfma_f32_16x16x32_bf16 v[34:37], v[156:159], v[176:179], 0
	v_mfma_f32_16x16x32_bf16 v[22:25], v[146:149], v[188:191], 0
	v_mfma_f32_16x16x32_bf16 v[18:21], v[156:159], v[188:191], 0
	v_mfma_f32_16x16x32_bf16 v[6:9], v[146:149], v[196:199], 0
	v_mfma_f32_16x16x32_bf16 v[2:5], v[156:159], v[196:199], 0
	v_mfma_f32_16x16x32_bf16 v[54:57], v[150:153], v[172:175], v[54:57]
	v_mfma_f32_16x16x32_bf16 v[50:53], v[160:163], v[172:175], v[50:53]
	v_mfma_f32_16x16x32_bf16 v[38:41], v[150:153], v[180:183], v[38:41]
	v_mfma_f32_16x16x32_bf16 v[34:37], v[160:163], v[180:183], v[34:37]
	v_mfma_f32_16x16x32_bf16 v[22:25], v[150:153], v[192:195], v[22:25]
	v_mfma_f32_16x16x32_bf16 v[18:21], v[160:163], v[192:195], v[18:21]
	v_mfma_f32_16x16x32_bf16 v[6:9], v[150:153], v[200:203], v[6:9]
	v_mfma_f32_16x16x32_bf16 v[2:5], v[160:163], v[200:203], v[2:5]
	s_setprio 0
	s_barrier
	v_add_u32_e32 v0, s31, v166
	ds_read_b128 v[130:133], v0
	ds_read_b128 v[134:137], v0 offset:1024
	ds_read_b128 v[138:141], v0 offset:2048
	ds_read_b128 v[142:145], v0 offset:3072
	v_add_u32_e32 v0, s39, v166
	ds_read_b128 v[146:149], v0
	ds_read_b128 v[150:153], v0 offset:1024
	ds_read_b128 v[156:159], v0 offset:2048
	ds_read_b128 v[160:163], v0 offset:3072
	s_mov_b32 m0, s28
	v_lshl_add_u64 v[206:207], v[204:205], 0, s[96:97]
	ds_read_b128 v[168:171], v167 offset:32768
	ds_read_b128 v[172:175], v167 offset:33792
	ds_read_b128 v[176:179], v167 offset:34816
	ds_read_b128 v[180:183], v167 offset:35840
	ds_read_b128 v[188:191], v167 offset:36864
	ds_read_b128 v[192:195], v167 offset:37888
	ds_read_b128 v[196:199], v167 offset:38912
	ds_read_b128 v[200:203], v167 offset:39936
	global_load_lds_dwordx4 v[206:207], off
	v_lshl_add_u64 v[206:207], v[204:205], 0, s[60:61]
	s_mov_b32 m0, s29
	s_nop 0
	global_load_lds_dwordx4 v[206:207], off
	s_waitcnt vmcnt(8)
	s_waitcnt lgkmcnt(0)
	s_barrier
	s_setprio 1
	s_waitcnt lgkmcnt(0)
	v_mfma_f32_16x16x32_bf16 v[126:129], v[130:133], v[168:171], v[126:129]
	v_mfma_f32_16x16x32_bf16 v[122:125], v[138:141], v[168:171], v[122:125]
	v_mfma_f32_16x16x32_bf16 v[110:113], v[130:133], v[176:179], v[110:113]
	v_mfma_f32_16x16x32_bf16 v[106:109], v[138:141], v[176:179], v[106:109]
	v_mfma_f32_16x16x32_bf16 v[94:97], v[130:133], v[188:191], v[94:97]
	v_mfma_f32_16x16x32_bf16 v[90:93], v[138:141], v[188:191], v[90:93]
	v_mfma_f32_16x16x32_bf16 v[78:81], v[130:133], v[196:199], v[78:81]
	v_mfma_f32_16x16x32_bf16 v[74:77], v[138:141], v[196:199], v[74:77]
	v_mfma_f32_16x16x32_bf16 v[126:129], v[134:137], v[172:175], v[126:129]
	v_mfma_f32_16x16x32_bf16 v[122:125], v[142:145], v[172:175], v[122:125]
	v_mfma_f32_16x16x32_bf16 v[110:113], v[134:137], v[180:183], v[110:113]
	v_mfma_f32_16x16x32_bf16 v[106:109], v[142:145], v[180:183], v[106:109]
	v_mfma_f32_16x16x32_bf16 v[94:97], v[134:137], v[192:195], v[94:97]
	v_mfma_f32_16x16x32_bf16 v[90:93], v[142:145], v[192:195], v[90:93]
	v_mfma_f32_16x16x32_bf16 v[78:81], v[134:137], v[200:203], v[78:81]
	v_mfma_f32_16x16x32_bf16 v[74:77], v[142:145], v[200:203], v[74:77]
	s_setprio 0
	s_setprio 1
	v_mfma_f32_16x16x32_bf16 v[118:121], v[146:149], v[168:171], v[118:121]
	v_mfma_f32_16x16x32_bf16 v[114:117], v[156:159], v[168:171], v[114:117]
	v_mfma_f32_16x16x32_bf16 v[102:105], v[146:149], v[176:179], v[102:105]
	v_mfma_f32_16x16x32_bf16 v[98:101], v[156:159], v[176:179], v[98:101]
	v_mfma_f32_16x16x32_bf16 v[86:89], v[146:149], v[188:191], v[86:89]
	v_mfma_f32_16x16x32_bf16 v[82:85], v[156:159], v[188:191], v[82:85]
	v_mfma_f32_16x16x32_bf16 v[70:73], v[146:149], v[196:199], v[70:73]
	v_mfma_f32_16x16x32_bf16 v[66:69], v[156:159], v[196:199], v[66:69]
	v_mfma_f32_16x16x32_bf16 v[118:121], v[150:153], v[172:175], v[118:121]
	v_mfma_f32_16x16x32_bf16 v[114:117], v[160:163], v[172:175], v[114:117]
	v_mfma_f32_16x16x32_bf16 v[102:105], v[150:153], v[180:183], v[102:105]
	v_mfma_f32_16x16x32_bf16 v[98:101], v[160:163], v[180:183], v[98:101]
	v_mfma_f32_16x16x32_bf16 v[86:89], v[150:153], v[192:195], v[86:89]
	v_mfma_f32_16x16x32_bf16 v[82:85], v[160:163], v[192:195], v[82:85]
	v_mfma_f32_16x16x32_bf16 v[70:73], v[150:153], v[200:203], v[70:73]
	v_mfma_f32_16x16x32_bf16 v[66:69], v[160:163], v[200:203], v[66:69]
	s_setprio 0
	s_barrier
; #define PG8_STAGE(bufoff, gbase, unused) do { _Pragma("unroll") for (int _i = 0; _i < 2; ++_i) \
;         __builtin_amdgcn_global_load_lds((const unsigned*)((const char*)(gbase) + voff + _i * 8192), (LAS unsigned*)(lds + (bufoff) + ldsw + _i * 8192), 16, 0, 0); } while (0)
; #define PG8_LDA(dst, b, h) do { _Pragma("unroll") for (int m = 0; m < 4; ++m) _Pragma("unroll") for (int k = 0; k < 2; ++k) dst[m][k] = *(const LAS bf16x8*)(lds + PG8_SA(b, h) + aoff + m * 2048 + (FP8 ? k * 16 : k * 1024)); } while (0)
; #define PG8_WAIT_V(n) asm volatile("s_waitcnt vmcnt(" #n ")" ::: "memory")
; #define PG8_WAIT_L(n) asm volatile("s_waitcnt lgkmcnt(" #n ")" ::: "memory")
; #define PG8_BAR __builtin_amdgcn_s_barrier()
; #define PG8_SCHED __builtin_amdgcn_sched_barrier(0)
; template <class Epi, class Sched, bool ALIGN_EPI, bool SP2, int MODE  >
; __device__ __forceinline__ void gemm_phase(LAS unsigned char* lds, const Gemm g, const Sched S, const Epi E, unsigned long long& probe_acc, int epi_id, int wv) {
;     ...
;             PG8_LDA(At, 1, 1); PG8_STAGE(PG8_SB(1, 0), b3, voffB); PG8_STAGE(PG8_SB(1, 1), b3 + hB, voffB); PG8_STAGE(PG8_SA(1, 0), a3, voffA);
;             PG8_WAIT_V(8); PG8_WAIT_L(0); PG8_BAR; PG8_MMA(1, 0, At, B0); PG8_MMA(1, 1, At, B1); PG8_BAR; PG8_SCHED;
	s_mov_b32 m0, s34
	v_lshl_add_u64 v[206:207], v[184:185], 0, s[76:77]
	ds_read_b128 v[168:171], v167 offset:49152
	ds_read_b128 v[172:175], v167 offset:50176
	ds_read_b128 v[176:179], v167 offset:51200
	ds_read_b128 v[180:183], v167 offset:52224
	ds_read_b128 v[188:191], v167 offset:53248
	ds_read_b128 v[192:195], v167 offset:54272
	ds_read_b128 v[196:199], v167 offset:55296
	ds_read_b128 v[200:203], v167 offset:56320
	global_load_lds_dwordx4 v[206:207], off
	v_lshl_add_u64 v[206:207], v[184:185], 0, s[78:79]
	s_mov_b32 m0, s35
	s_nop 0
	global_load_lds_dwordx4 v[206:207], off
	v_lshl_add_u64 v[206:207], v[184:185], 0, s[52:53]
	s_mov_b32 m0, s40
	v_lshl_add_u64 v[184:185], v[184:185], 0, s[54:55]
	global_load_lds_dwordx4 v[206:207], off
	s_mov_b32 m0, s41
	s_nop 0
	global_load_lds_dwordx4 v[184:185], off
	v_lshl_add_u64 v[184:185], v[204:205], 0, s[76:77]
	s_mov_b32 m0, s36
	s_nop 0
	global_load_lds_dwordx4 v[184:185], off
	v_lshl_add_u64 v[184:185], v[204:205], 0, s[78:79]
	s_mov_b32 m0, s37
	s_nop 0
	global_load_lds_dwordx4 v[184:185], off
	s_waitcnt vmcnt(8)
	s_waitcnt lgkmcnt(0)
	s_barrier
	s_setprio 1
	s_waitcnt lgkmcnt(0)
	v_mfma_f32_16x16x32_bf16 v[62:65], v[130:133], v[168:171], v[62:65]
	v_mfma_f32_16x16x32_bf16 v[58:61], v[138:141], v[168:171], v[58:61]
	v_mfma_f32_16x16x32_bf16 v[46:49], v[130:133], v[176:179], v[46:49]
	v_mfma_f32_16x16x32_bf16 v[42:45], v[138:141], v[176:179], v[42:45]
	v_mfma_f32_16x16x32_bf16 v[30:33], v[130:133], v[188:191], v[30:33]
	v_mfma_f32_16x16x32_bf16 v[26:29], v[138:141], v[188:191], v[26:29]
	v_mfma_f32_16x16x32_bf16 v[14:17], v[130:133], v[196:199], v[14:17]
	v_mfma_f32_16x16x32_bf16 v[10:13], v[138:141], v[196:199], v[10:13]
	v_mfma_f32_16x16x32_bf16 v[62:65], v[134:137], v[172:175], v[62:65]
	v_mfma_f32_16x16x32_bf16 v[58:61], v[142:145], v[172:175], v[58:61]
	v_mfma_f32_16x16x32_bf16 v[46:49], v[134:137], v[180:183], v[46:49]
	v_mfma_f32_16x16x32_bf16 v[42:45], v[142:145], v[180:183], v[42:45]
	v_mfma_f32_16x16x32_bf16 v[30:33], v[134:137], v[192:195], v[30:33]
	v_mfma_f32_16x16x32_bf16 v[26:29], v[142:145], v[192:195], v[26:29]
	v_mfma_f32_16x16x32_bf16 v[14:17], v[134:137], v[200:203], v[14:17]
	v_mfma_f32_16x16x32_bf16 v[10:13], v[142:145], v[200:203], v[10:13]
	s_setprio 0
	s_setprio 1
	v_mfma_f32_16x16x32_bf16 v[54:57], v[146:149], v[168:171], v[54:57]
	v_mfma_f32_16x16x32_bf16 v[50:53], v[156:159], v[168:171], v[50:53]
	v_mfma_f32_16x16x32_bf16 v[38:41], v[146:149], v[176:179], v[38:41]
	v_mfma_f32_16x16x32_bf16 v[34:37], v[156:159], v[176:179], v[34:37]
	v_mfma_f32_16x16x32_bf16 v[22:25], v[146:149], v[188:191], v[22:25]
	v_mfma_f32_16x16x32_bf16 v[18:21], v[156:159], v[188:191], v[18:21]
	v_mfma_f32_16x16x32_bf16 v[6:9], v[146:149], v[196:199], v[6:9]
	v_mfma_f32_16x16x32_bf16 v[2:5], v[156:159], v[196:199], v[2:5]
	v_mfma_f32_16x16x32_bf16 v[54:57], v[150:153], v[172:175], v[54:57]
	v_mfma_f32_16x16x32_bf16 v[50:53], v[160:163], v[172:175], v[50:53]
	v_mfma_f32_16x16x32_bf16 v[38:41], v[150:153], v[180:183], v[38:41]
	v_mfma_f32_16x16x32_bf16 v[34:37], v[160:163], v[180:183], v[34:37]
	v_mfma_f32_16x16x32_bf16 v[22:25], v[150:153], v[192:195], v[22:25]
	v_mfma_f32_16x16x32_bf16 v[18:21], v[160:163], v[192:195], v[18:21]
	v_mfma_f32_16x16x32_bf16 v[6:9], v[150:153], v[200:203], v[6:9]
	v_mfma_f32_16x16x32_bf16 v[2:5], v[160:163], v[200:203], v[2:5]
	s_setprio 0
	s_barrier
	s_add_i32 s95, s95, 2
	s_add_u32 s93, s93, 0x8000
	s_addc_u32 s94, s94, 0
	s_cmp_gt_u32 s95, 29
	s_mov_b64 s[18:19], s[20:21]

;     __device__ __forceinline__ bool next(int i, Unit& u) const { const int off = i * H + (r >> 1); if (off >= 8 * nN) return false; u.pm = 16 * g + 8 * (r & 1) + (off & 7); u.pn = off >> 3; return true; }
; #define PG8_STAGE(bufoff, gbase, unused) do { _Pragma("unroll") for (int _i = 0; _i < 2; ++_i) \
;         __builtin_amdgcn_global_load_lds((const unsigned*)((const char*)(gbase) + voff + _i * 8192), (LAS unsigned*)(lds + (bufoff) + ldsw + _i * 8192), 16, 0, 0); } while (0)
; #define PG8_LDA(dst, b, h) do { _Pragma("unroll") for (int m = 0; m < 4; ++m) _Pragma("unroll") for (int k = 0; k < 2; ++k) dst[m][k] = *(const LAS bf16x8*)(lds + PG8_SA(b, h) + aoff + m * 2048 + (FP8 ? k * 16 : k * 1024)); } while (0)
; #define PG8_LDB(dst, b, h) do { _Pragma("unroll") for (int n = 0; n < 2; ++n) _Pragma("unroll") for (int k = 0; k < 2; ++k) dst[n][k] = *(const LAS bf16x8*)(lds + PG8_SB(b, h) + boff + n * 2048 + (FP8 ? k * 16 : k * 1024)); } while (0)
; template <class Epi, class Sched, bool ALIGN_EPI, bool SP2, int MODE  >
; __device__ __forceinline__ void gemm_phase(LAS unsigned char* lds, const Gemm g, const Sched S, const Epi E, unsigned long long& probe_acc, int epi_id, int wv) {
;     ...
;     for (;;) {
;         const bool has_next = S.next(ui + 1, nxt);
;         const char* nA = has_next ? (const char*)g.A + (size_t)nxt.pm * tA + (g.gt ? (size_t)(nxt.pn / g.gt) * gK2 : 0) : cA; const char* nB = has_next ? (const char*)g.Bt + (size_t)nxt.pn * tB : cB;
;         for (int t = 0; t < nt; t += 2) {
;             const bool last = (t == nt - 2);
;             const char* a1 = cA + (size_t)(t + 1) * kstep;
;             const char* a2 = last ? nA : cA + (size_t)(t + 2) * kstep; const char* b2 = last ? nB : cB + (size_t)(t + 2) * kstep;
;             const char* a3 = a2 + kstep; const char* b3 = b2 + kstep;
;             if constexpr (SP2) {
;             PG8_LDB(B0, 0, 0); PG8_LDB(B1, 0, 1); PG8_SCHED; PG8_LDA(At, 0, 0); PG8_STAGE(PG8_SA(1, 1), a1 + hA, voffA);
;             PG8_WAIT_V(8); PG8_WAIT_L(0); PG8_BAR; PG8_MMA(0, 0, At, B0); PG8_MMA(0, 1, At, B1); PG8_BAR; PG8_SCHED;
;             PG8_LDA(At, 0, 1); PG8_STAGE(PG8_SB(0, 0), b2, voffB); PG8_STAGE(PG8_SB(0, 1), b2 + hB, voffB); PG8_STAGE(PG8_SA(0, 0), a2, voffA);
;             PG8_WAIT_V(8); PG8_WAIT_L(0); PG8_BAR; PG8_MMA(1, 0, At, B0); PG8_MMA(1, 1, At, B1); PG8_BAR; PG8_SCHED;
.LBB0_673:
	s_add_u32 s10, s4, 0x8000
	s_addc_u32 s11, s5, 0
	s_add_u32 s4, s6, 0x8000
	s_addc_u32 s5, s7, 0
	s_mov_b32 s6, 0
	s_waitcnt lgkmcnt(0)
	s_waitcnt vmcnt(0)
	v_add_u32_e32 v142, s15, v193
	v_add_u32_e32 v156, s39, v193
	ds_read_b128 v[130:133], v142
	ds_read_b128 v[134:137], v142 offset:1024
	ds_read_b128 v[138:141], v142 offset:2048
	ds_read_b128 v[142:145], v142 offset:3072
	ds_read_b128 v[146:149], v156
	ds_read_b128 v[150:153], v156 offset:1024
	ds_read_b128 v[158:161], v156 offset:2048
	ds_read_b128 v[162:165], v156 offset:3072
	s_add_i32 s40, s6, 2
	s_cmp_eq_u32 s93, s6
	s_cselect_b32 s6, s34, s10
	s_cselect_b32 s9, s87, s5
	s_cselect_b32 s8, s86, s4
	s_cselect_b32 s7, s35, s11
	s_movk_i32 vcc_lo, 0xc000
	v_lshl_add_u64 v[190:191], s[4:5], 0, v[154:155]
	s_mov_b32 vcc_hi, -1
	v_lshl_add_u64 v[196:197], v[190:191], 0, vcc
	s_movk_i32 vcc_lo, 0xe000
	s_add_i32 m0, s88, 0xc000
	s_mov_b32 vcc_hi, -1
	ds_read_b128 v[166:169], v194
	ds_read_b128 v[170:173], v194 offset:1024
	ds_read_b128 v[174:177], v194 offset:2048
	ds_read_b128 v[178:181], v194 offset:3072
	ds_read_b128 v[182:185], v194 offset:4096
	ds_read_b128 v[186:189], v194 offset:5120
	ds_read_b128 v[200:203], v194 offset:6144
	ds_read_b128 v[204:207], v194 offset:7168
	global_load_lds_dwordx4 v[196:197], off
	v_lshl_add_u64 v[190:191], v[190:191], 0, vcc
	s_add_i32 m0, s88, 0xe000
	s_nop 0
	global_load_lds_dwordx4 v[190:191], off
	s_waitcnt vmcnt(8)
	s_waitcnt lgkmcnt(0)
	s_barrier
	s_setprio 1
	s_waitcnt lgkmcnt(0)
	v_mfma_f32_16x16x32_bf16 v[126:129], v[130:133], v[166:169], 0
	v_mfma_f32_16x16x32_bf16 v[122:125], v[138:141], v[166:169], 0
	v_mfma_f32_16x16x32_bf16 v[118:121], v[130:133], v[174:177], 0
	v_mfma_f32_16x16x32_bf16 v[114:117], v[138:141], v[174:177], 0
	v_mfma_f32_16x16x32_bf16 v[110:113], v[130:133], v[182:185], 0
	v_mfma_f32_16x16x32_bf16 v[106:109], v[138:141], v[182:185], 0
	v_mfma_f32_16x16x32_bf16 v[102:105], v[130:133], v[200:203], 0
	v_mfma_f32_16x16x32_bf16 v[98:101], v[138:141], v[200:203], 0
	v_mfma_f32_16x16x32_bf16 v[126:129], v[134:137], v[170:173], v[126:129]
	v_mfma_f32_16x16x32_bf16 v[122:125], v[142:145], v[170:173], v[122:125]
	v_mfma_f32_16x16x32_bf16 v[118:121], v[134:137], v[178:181], v[118:121]
	v_mfma_f32_16x16x32_bf16 v[114:117], v[142:145], v[178:181], v[114:117]
	v_mfma_f32_16x16x32_bf16 v[110:113], v[134:137], v[186:189], v[110:113]
	v_mfma_f32_16x16x32_bf16 v[106:109], v[142:145], v[186:189], v[106:109]
	v_mfma_f32_16x16x32_bf16 v[102:105], v[134:137], v[204:207], v[102:105]
	v_mfma_f32_16x16x32_bf16 v[98:101], v[142:145], v[204:207], v[98:101]
	s_setprio 0
	s_setprio 1
	v_mfma_f32_16x16x32_bf16 v[62:65], v[146:149], v[166:169], 0
	v_mfma_f32_16x16x32_bf16 v[58:61], v[158:161], v[166:169], 0
	v_mfma_f32_16x16x32_bf16 v[54:57], v[146:149], v[174:177], 0
	v_mfma_f32_16x16x32_bf16 v[50:53], v[158:161], v[174:177], 0
	v_mfma_f32_16x16x32_bf16 v[46:49], v[146:149], v[182:185], 0
	v_mfma_f32_16x16x32_bf16 v[42:45], v[158:161], v[182:185], 0
	v_mfma_f32_16x16x32_bf16 v[38:41], v[146:149], v[200:203], 0
	v_mfma_f32_16x16x32_bf16 v[34:37], v[158:161], v[200:203], 0
	v_mfma_f32_16x16x32_bf16 v[62:65], v[150:153], v[170:173], v[62:65]
	v_mfma_f32_16x16x32_bf16 v[58:61], v[162:165], v[170:173], v[58:61]
	v_mfma_f32_16x16x32_bf16 v[54:57], v[150:153], v[178:181], v[54:57]
	v_mfma_f32_16x16x32_bf16 v[50:53], v[162:165], v[178:181], v[50:53]
	v_mfma_f32_16x16x32_bf16 v[46:49], v[150:153], v[186:189], v[46:49]
	v_mfma_f32_16x16x32_bf16 v[42:45], v[162:165], v[186:189], v[42:45]
	v_mfma_f32_16x16x32_bf16 v[38:41], v[150:153], v[204:207], v[38:41]
	v_mfma_f32_16x16x32_bf16 v[34:37], v[162:165], v[204:207], v[34:37]
	s_setprio 0
	s_barrier
	s_mov_b32 m0, s26
	v_lshl_add_u64 v[190:191], s[6:7], 0, v[0:1]
	s_add_u32 vcc_lo, s6, s13
	ds_read_b128 v[166:169], v194 offset:16384
	ds_read_b128 v[170:173], v194 offset:17408
	ds_read_b128 v[174:177], v194 offset:18432
	ds_read_b128 v[178:181], v194 offset:19456
	ds_read_b128 v[182:185], v194 offset:20480
	ds_read_b128 v[186:189], v194 offset:21504
	ds_read_b128 v[200:203], v194 offset:22528
	ds_read_b128 v[204:207], v194 offset:23552
	global_load_lds_dwordx4 v[190:191], off
	v_lshl_add_u64 v[190:191], v[190:191], 0, s[70:71]
	s_mov_b32 m0, s27
	s_addc_u32 vcc_hi, s7, 0
	global_load_lds_dwordx4 v[190:191], off
	v_lshl_add_u64 v[190:191], vcc, 0, v[0:1]
	s_mov_b32 m0, s84
	s_nop 0
	global_load_lds_dwordx4 v[190:191], off
	v_lshl_add_u64 v[190:191], v[190:191], 0, s[70:71]
	s_mov_b32 m0, s85
	s_nop 0
	global_load_lds_dwordx4 v[190:191], off
	v_lshl_add_u64 v[190:191], s[8:9], 0, v[0:1]
	s_mov_b32 m0, s88
	v_lshl_add_u64 v[196:197], v[190:191], 0, s[70:71]
	global_load_lds_dwordx4 v[190:191], off
	s_mov_b32 m0, s89
	s_nop 0
	global_load_lds_dwordx4 v[196:197], off
	s_waitcnt vmcnt(8)
	s_waitcnt lgkmcnt(0)
	s_barrier
; #define PG8_STAGE(bufoff, gbase, unused) do { _Pragma("unroll") for (int _i = 0; _i < 2; ++_i) \
;         __builtin_amdgcn_global_load_lds((const unsigned*)((const char*)(gbase) + voff + _i * 8192), (LAS unsigned*)(lds + (bufoff) + ldsw + _i * 8192), 16, 0, 0); } while (0)
; #define PG8_LDA(dst, b, h) do { _Pragma("unroll") for (int m = 0; m < 4; ++m) _Pragma("unroll") for (int k = 0; k < 2; ++k) dst[m][k] = *(const LAS bf16x8*)(lds + PG8_SA(b, h) + aoff + m * 2048 + (FP8 ? k * 16 : k * 1024)); } while (0)
; #define PG8_LDB(dst, b, h) do { _Pragma("unroll") for (int n = 0; n < 2; ++n) _Pragma("unroll") for (int k = 0; k < 2; ++k) dst[n][k] = *(const LAS bf16x8*)(lds + PG8_SB(b, h) + boff + n * 2048 + (FP8 ? k * 16 : k * 1024)); } while (0)
; #define PG8_WAIT_V(n) asm volatile("s_waitcnt vmcnt(" #n ")" ::: "memory")
; #define PG8_WAIT_L(n) asm volatile("s_waitcnt lgkmcnt(" #n ")" ::: "memory")
; #define PG8_BAR __builtin_amdgcn_s_barrier()
; #define PG8_SCHED __builtin_amdgcn_sched_barrier(0)
; template <class Epi, class Sched, bool ALIGN_EPI, bool SP2, int MODE  >
; __device__ __forceinline__ void gemm_phase(LAS unsigned char* lds, const Gemm g, const Sched S, const Epi E, unsigned long long& probe_acc, int epi_id, int wv) {
;     ...
;             PG8_WAIT_V(8); PG8_WAIT_L(0); PG8_BAR; PG8_MMA(1, 0, At, B0); PG8_MMA(1, 1, At, B1); PG8_BAR; PG8_SCHED;
;             PG8_LDB(B0, 1, 0); PG8_LDB(B1, 1, 1); PG8_SCHED; PG8_LDA(At, 1, 0); PG8_STAGE(PG8_SA(0, 1), a2 + hA, voffA);
;             PG8_WAIT_V(8); PG8_WAIT_L(0); PG8_BAR; PG8_MMA(0, 0, At, B0); PG8_MMA(0, 1, At, B1); PG8_BAR; PG8_SCHED;
;             PG8_LDA(At, 1, 1); PG8_STAGE(PG8_SB(1, 0), b3, voffB); PG8_STAGE(PG8_SB(1, 1), b3 + hB, voffB); PG8_STAGE(PG8_SA(1, 0), a3, voffA);
	s_setprio 1
	s_waitcnt lgkmcnt(0)
	v_mfma_f32_16x16x32_bf16 v[94:97], v[130:133], v[166:169], 0
	v_mfma_f32_16x16x32_bf16 v[90:93], v[138:141], v[166:169], 0
	v_mfma_f32_16x16x32_bf16 v[86:89], v[130:133], v[174:177], 0
	v_mfma_f32_16x16x32_bf16 v[82:85], v[138:141], v[174:177], 0
	v_mfma_f32_16x16x32_bf16 v[78:81], v[130:133], v[182:185], 0
	v_mfma_f32_16x16x32_bf16 v[74:77], v[138:141], v[182:185], 0
	v_mfma_f32_16x16x32_bf16 v[70:73], v[130:133], v[200:203], 0
	v_mfma_f32_16x16x32_bf16 v[66:69], v[138:141], v[200:203], 0
	v_mfma_f32_16x16x32_bf16 v[94:97], v[134:137], v[170:173], v[94:97]
	v_mfma_f32_16x16x32_bf16 v[90:93], v[142:145], v[170:173], v[90:93]
	v_mfma_f32_16x16x32_bf16 v[86:89], v[134:137], v[178:181], v[86:89]
	v_mfma_f32_16x16x32_bf16 v[82:85], v[142:145], v[178:181], v[82:85]
	v_mfma_f32_16x16x32_bf16 v[78:81], v[134:137], v[186:189], v[78:81]
	v_mfma_f32_16x16x32_bf16 v[74:77], v[142:145], v[186:189], v[74:77]
	v_mfma_f32_16x16x32_bf16 v[70:73], v[134:137], v[204:207], v[70:73]
	v_mfma_f32_16x16x32_bf16 v[66:69], v[142:145], v[204:207], v[66:69]
	s_setprio 0
	s_setprio 1
	v_mfma_f32_16x16x32_bf16 v[30:33], v[146:149], v[166:169], 0
	v_mfma_f32_16x16x32_bf16 v[26:29], v[158:161], v[166:169], 0
	v_mfma_f32_16x16x32_bf16 v[22:25], v[146:149], v[174:177], 0
	v_mfma_f32_16x16x32_bf16 v[18:21], v[158:161], v[174:177], 0
	v_mfma_f32_16x16x32_bf16 v[14:17], v[146:149], v[182:185], 0
	v_mfma_f32_16x16x32_bf16 v[10:13], v[158:161], v[182:185], 0
	v_mfma_f32_16x16x32_bf16 v[6:9], v[146:149], v[200:203], 0
	v_mfma_f32_16x16x32_bf16 v[2:5], v[158:161], v[200:203], 0
	v_mfma_f32_16x16x32_bf16 v[30:33], v[150:153], v[170:173], v[30:33]
	v_mfma_f32_16x16x32_bf16 v[26:29], v[162:165], v[170:173], v[26:29]
	v_mfma_f32_16x16x32_bf16 v[22:25], v[150:153], v[178:181], v[22:25]
	v_mfma_f32_16x16x32_bf16 v[18:21], v[162:165], v[178:181], v[18:21]
	v_mfma_f32_16x16x32_bf16 v[14:17], v[150:153], v[186:189], v[14:17]
	v_mfma_f32_16x16x32_bf16 v[10:13], v[162:165], v[186:189], v[10:13]
	v_mfma_f32_16x16x32_bf16 v[6:9], v[150:153], v[204:207], v[6:9]
	v_mfma_f32_16x16x32_bf16 v[2:5], v[162:165], v[204:207], v[2:5]
	s_setprio 0
	s_barrier
	v_add_u32_e32 v142, s28, v193
	v_add_u32_e32 v156, s94, v193
	ds_read_b128 v[130:133], v142
	ds_read_b128 v[134:137], v142 offset:1024
	ds_read_b128 v[138:141], v142 offset:2048
	ds_read_b128 v[142:145], v142 offset:3072
	ds_read_b128 v[146:149], v156
	ds_read_b128 v[150:153], v156 offset:1024
	ds_read_b128 v[158:161], v156 offset:2048
	ds_read_b128 v[162:165], v156 offset:3072
	s_add_u32 s8, s8, s36
	s_addc_u32 s9, s9, 0
	s_mov_b32 m0, s29
	v_lshl_add_u64 v[196:197], s[8:9], 0, v[0:1]
	ds_read_b128 v[166:169], v194 offset:32768
	ds_read_b128 v[170:173], v194 offset:33792
	ds_read_b128 v[174:177], v194 offset:34816
	ds_read_b128 v[178:181], v194 offset:35840
	ds_read_b128 v[182:185], v194 offset:36864
	ds_read_b128 v[186:189], v194 offset:37888
	ds_read_b128 v[200:203], v194 offset:38912
	ds_read_b128 v[204:207], v194 offset:39936
	global_load_lds_dwordx4 v[196:197], off
	v_lshl_add_u64 v[196:197], v[196:197], 0, s[70:71]
	s_mov_b32 m0, s92
	s_nop 0
	global_load_lds_dwordx4 v[196:197], off
	s_waitcnt vmcnt(8)
	s_waitcnt lgkmcnt(0)
	s_barrier
	s_setprio 1
	s_waitcnt lgkmcnt(0)
	v_mfma_f32_16x16x32_bf16 v[126:129], v[130:133], v[166:169], v[126:129]
	v_mfma_f32_16x16x32_bf16 v[122:125], v[138:141], v[166:169], v[122:125]
	v_mfma_f32_16x16x32_bf16 v[118:121], v[130:133], v[174:177], v[118:121]
	v_mfma_f32_16x16x32_bf16 v[114:117], v[138:141], v[174:177], v[114:117]
	v_mfma_f32_16x16x32_bf16 v[110:113], v[130:133], v[182:185], v[110:113]
	v_mfma_f32_16x16x32_bf16 v[106:109], v[138:141], v[182:185], v[106:109]
	v_mfma_f32_16x16x32_bf16 v[102:105], v[130:133], v[200:203], v[102:105]
	v_mfma_f32_16x16x32_bf16 v[98:101], v[138:141], v[200:203], v[98:101]
	v_mfma_f32_16x16x32_bf16 v[126:129], v[134:137], v[170:173], v[126:129]
	v_mfma_f32_16x16x32_bf16 v[122:125], v[142:145], v[170:173], v[122:125]
	v_mfma_f32_16x16x32_bf16 v[118:121], v[134:137], v[178:181], v[118:121]
	v_mfma_f32_16x16x32_bf16 v[114:117], v[142:145], v[178:181], v[114:117]
	v_mfma_f32_16x16x32_bf16 v[110:113], v[134:137], v[186:189], v[110:113]
	v_mfma_f32_16x16x32_bf16 v[106:109], v[142:145], v[186:189], v[106:109]
	v_mfma_f32_16x16x32_bf16 v[102:105], v[134:137], v[204:207], v[102:105]
	v_mfma_f32_16x16x32_bf16 v[98:101], v[142:145], v[204:207], v[98:101]
	s_setprio 0
	s_setprio 1
	v_mfma_f32_16x16x32_bf16 v[62:65], v[146:149], v[166:169], v[62:65]
	v_mfma_f32_16x16x32_bf16 v[58:61], v[158:161], v[166:169], v[58:61]
	v_mfma_f32_16x16x32_bf16 v[54:57], v[146:149], v[174:177], v[54:57]
	v_mfma_f32_16x16x32_bf16 v[50:53], v[158:161], v[174:177], v[50:53]
	v_mfma_f32_16x16x32_bf16 v[46:49], v[146:149], v[182:185], v[46:49]
	v_mfma_f32_16x16x32_bf16 v[42:45], v[158:161], v[182:185], v[42:45]
	v_mfma_f32_16x16x32_bf16 v[38:41], v[146:149], v[200:203], v[38:41]
	v_mfma_f32_16x16x32_bf16 v[34:37], v[158:161], v[200:203], v[34:37]
	v_mfma_f32_16x16x32_bf16 v[62:65], v[150:153], v[170:173], v[62:65]
	v_mfma_f32_16x16x32_bf16 v[58:61], v[162:165], v[170:173], v[58:61]
	v_mfma_f32_16x16x32_bf16 v[54:57], v[150:153], v[178:181], v[54:57]
	v_mfma_f32_16x16x32_bf16 v[50:53], v[162:165], v[178:181], v[50:53]
	v_mfma_f32_16x16x32_bf16 v[46:49], v[150:153], v[186:189], v[46:49]
	v_mfma_f32_16x16x32_bf16 v[42:45], v[162:165], v[186:189], v[42:45]
	v_mfma_f32_16x16x32_bf16 v[38:41], v[150:153], v[204:207], v[38:41]
	v_mfma_f32_16x16x32_bf16 v[34:37], v[162:165], v[204:207], v[34:37]
	s_setprio 0
	s_barrier
; #define PG8_STAGE(bufoff, gbase, unused) do { _Pragma("unroll") for (int _i = 0; _i < 2; ++_i) \
;         __builtin_amdgcn_global_load_lds((const unsigned*)((const char*)(gbase) + voff + _i * 8192), (LAS unsigned*)(lds + (bufoff) + ldsw + _i * 8192), 16, 0, 0); } while (0)
; #define PG8_LDA(dst, b, h) do { _Pragma("unroll") for (int m = 0; m < 4; ++m) _Pragma("unroll") for (int k = 0; k < 2; ++k) dst[m][k] = *(const LAS bf16x8*)(lds + PG8_SA(b, h) + aoff + m * 2048 + (FP8 ? k * 16 : k * 1024)); } while (0)
; #define PG8_WAIT_V(n) asm volatile("s_waitcnt vmcnt(" #n ")" ::: "memory")
; #define PG8_WAIT_L(n) asm volatile("s_waitcnt lgkmcnt(" #n ")" ::: "memory")
; #define PG8_BAR __builtin_amdgcn_s_barrier()
; #define PG8_SCHED __builtin_amdgcn_sched_barrier(0)
; template <class Epi, class Sched, bool ALIGN_EPI, bool SP2, int MODE  >
; __device__ __forceinline__ void gemm_phase(LAS unsigned char* lds, const Gemm g, const Sched S, const Epi E, unsigned long long& probe_acc, int epi_id, int wv) {
;     ...
;             PG8_LDA(At, 1, 1); PG8_STAGE(PG8_SB(1, 0), b3, voffB); PG8_STAGE(PG8_SB(1, 1), b3 + hB, voffB); PG8_STAGE(PG8_SA(1, 0), a3, voffA);
;             PG8_WAIT_V(8); PG8_WAIT_L(0); PG8_BAR; PG8_MMA(1, 0, At, B0); PG8_MMA(1, 1, At, B1); PG8_BAR; PG8_SCHED;
	s_add_u32 s6, s6, 0x4000
	s_addc_u32 s7, s7, 0
	s_mov_b32 m0, s2
	v_lshl_add_u64 v[196:197], s[6:7], 0, v[0:1]
	s_add_u32 s6, s6, s13
	ds_read_b128 v[166:169], v194 offset:49152
	ds_read_b128 v[170:173], v194 offset:50176
	ds_read_b128 v[174:177], v194 offset:51200
	ds_read_b128 v[178:181], v194 offset:52224
	ds_read_b128 v[182:185], v194 offset:53248
	ds_read_b128 v[186:189], v194 offset:54272
	ds_read_b128 v[200:203], v194 offset:55296
	ds_read_b128 v[204:207], v194 offset:56320
	global_load_lds_dwordx4 v[196:197], off
	v_lshl_add_u64 v[196:197], v[196:197], 0, s[70:71]
	s_mov_b32 m0, s3
	s_addc_u32 s7, s7, 0
	global_load_lds_dwordx4 v[196:197], off
	v_lshl_add_u64 v[196:197], s[6:7], 0, v[0:1]
	s_mov_b32 m0, s12
	s_nop 0
	global_load_lds_dwordx4 v[196:197], off
	v_lshl_add_u64 v[196:197], v[196:197], 0, s[70:71]
	s_mov_b32 m0, s95
	s_nop 0
	global_load_lds_dwordx4 v[196:197], off
	v_lshl_add_u64 v[196:197], v[190:191], 0, s[76:77]
	s_mov_b32 m0, s50
	v_lshl_add_u64 v[190:191], v[190:191], 0, s[78:79]
	global_load_lds_dwordx4 v[196:197], off
	s_mov_b32 m0, s51
	s_nop 0
	global_load_lds_dwordx4 v[190:191], off
	s_waitcnt vmcnt(8)
	s_waitcnt lgkmcnt(0)
	s_barrier
	s_setprio 1
	s_waitcnt lgkmcnt(0)
	v_mfma_f32_16x16x32_bf16 v[94:97], v[130:133], v[166:169], v[94:97]
	v_mfma_f32_16x16x32_bf16 v[90:93], v[138:141], v[166:169], v[90:93]
	v_mfma_f32_16x16x32_bf16 v[86:89], v[130:133], v[174:177], v[86:89]
	v_mfma_f32_16x16x32_bf16 v[82:85], v[138:141], v[174:177], v[82:85]
	v_mfma_f32_16x16x32_bf16 v[78:81], v[130:133], v[182:185], v[78:81]
	v_mfma_f32_16x16x32_bf16 v[74:77], v[138:141], v[182:185], v[74:77]
	v_mfma_f32_16x16x32_bf16 v[70:73], v[130:133], v[200:203], v[70:73]
	v_mfma_f32_16x16x32_bf16 v[66:69], v[138:141], v[200:203], v[66:69]
	v_mfma_f32_16x16x32_bf16 v[94:97], v[134:137], v[170:173], v[94:97]
	v_mfma_f32_16x16x32_bf16 v[90:93], v[142:145], v[170:173], v[90:93]
	v_mfma_f32_16x16x32_bf16 v[86:89], v[134:137], v[178:181], v[86:89]
	v_mfma_f32_16x16x32_bf16 v[82:85], v[142:145], v[178:181], v[82:85]
	v_mfma_f32_16x16x32_bf16 v[78:81], v[134:137], v[186:189], v[78:81]
	v_mfma_f32_16x16x32_bf16 v[74:77], v[142:145], v[186:189], v[74:77]
	v_mfma_f32_16x16x32_bf16 v[70:73], v[134:137], v[204:207], v[70:73]
	v_mfma_f32_16x16x32_bf16 v[66:69], v[142:145], v[204:207], v[66:69]
	s_setprio 0
	s_setprio 1
	v_mfma_f32_16x16x32_bf16 v[30:33], v[146:149], v[166:169], v[30:33]
	v_mfma_f32_16x16x32_bf16 v[26:29], v[158:161], v[166:169], v[26:29]
	v_mfma_f32_16x16x32_bf16 v[22:25], v[146:149], v[174:177], v[22:25]
	v_mfma_f32_16x16x32_bf16 v[18:21], v[158:161], v[174:177], v[18:21]
	v_mfma_f32_16x16x32_bf16 v[14:17], v[146:149], v[182:185], v[14:17]
	v_mfma_f32_16x16x32_bf16 v[10:13], v[158:161], v[182:185], v[10:13]
	v_mfma_f32_16x16x32_bf16 v[6:9], v[146:149], v[200:203], v[6:9]
	v_mfma_f32_16x16x32_bf16 v[2:5], v[158:161], v[200:203], v[2:5]
	v_mfma_f32_16x16x32_bf16 v[30:33], v[150:153], v[170:173], v[30:33]
	v_mfma_f32_16x16x32_bf16 v[26:29], v[162:165], v[170:173], v[26:29]
	v_mfma_f32_16x16x32_bf16 v[22:25], v[150:153], v[178:181], v[22:25]
	v_mfma_f32_16x16x32_bf16 v[18:21], v[162:165], v[178:181], v[18:21]
	v_mfma_f32_16x16x32_bf16 v[14:17], v[150:153], v[186:189], v[14:17]
	v_mfma_f32_16x16x32_bf16 v[10:13], v[162:165], v[186:189], v[10:13]
	v_mfma_f32_16x16x32_bf16 v[6:9], v[150:153], v[204:207], v[6:9]
	v_mfma_f32_16x16x32_bf16 v[2:5], v[162:165], v[204:207], v[2:5]
	s_setprio 0
	s_barrier
	s_add_u32 s10, s10, 0x8000
	s_addc_u32 s11, s11, 0
	s_add_u32 s4, s4, 0x8000
	s_addc_u32 s5, s5, 0
	s_cmp_ge_u32 s40, s58
	s_mov_b32 s6, s40

;     __device__ __forceinline__ bool next(int i, Unit& u) const { const int off = i * H + (r >> 1); if (off >= 8 * nN) return false; u.pm = 16 * g + 8 * (r & 1) + (off & 7); u.pn = off >> 3; return true; }
; #define PG8_STAGE(bufoff, gbase, unused) do { _Pragma("unroll") for (int _i = 0; _i < 2; ++_i) \
;         __builtin_amdgcn_global_load_lds((const unsigned*)((const char*)(gbase) + voff + _i * 8192), (LAS unsigned*)(lds + (bufoff) + ldsw + _i * 8192), 16, 0, 0); } while (0)
; #define PG8_LDA(dst, b, h) do { _Pragma("unroll") for (int m = 0; m < 4; ++m) _Pragma("unroll") for (int k = 0; k < 2; ++k) dst[m][k] = *(const LAS bf16x8*)(lds + PG8_SA(b, h) + aoff + m * 2048 + (FP8 ? k * 16 : k * 1024)); } while (0)
; #define PG8_LDB(dst, b, h) do { _Pragma("unroll") for (int n = 0; n < 2; ++n) _Pragma("unroll") for (int k = 0; k < 2; ++k) dst[n][k] = *(const LAS bf16x8*)(lds + PG8_SB(b, h) + boff + n * 2048 + (FP8 ? k * 16 : k * 1024)); } while (0)
; template <class Epi, class Sched, bool ALIGN_EPI, bool SP2, int MODE  >
; __device__ __forceinline__ void gemm_phase(LAS unsigned char* lds, const Gemm g, const Sched S, const Epi E, unsigned long long& probe_acc, int epi_id, int wv) {
;     ...
;     for (;;) {
;         const bool has_next = S.next(ui + 1, nxt);
;         const char* nA = has_next ? (const char*)g.A + (size_t)nxt.pm * tA + (g.gt ? (size_t)(nxt.pn / g.gt) * gK2 : 0) : cA; const char* nB = has_next ? (const char*)g.Bt + (size_t)nxt.pn * tB : cB;
;         for (int t = 0; t < nt; t += 2) {
;             const bool last = (t == nt - 2);
;             const char* a1 = cA + (size_t)(t + 1) * kstep;
;             const char* a2 = last ? nA : cA + (size_t)(t + 2) * kstep; const char* b2 = last ? nB : cB + (size_t)(t + 2) * kstep;
;             const char* a3 = a2 + kstep; const char* b3 = b2 + kstep;
;             if constexpr (SP2) {
;             PG8_LDB(B0, 0, 0); PG8_LDB(B1, 0, 1); PG8_SCHED; PG8_LDA(At, 0, 0); PG8_STAGE(PG8_SA(1, 1), a1 + hA, voffA);
;             PG8_WAIT_V(8); PG8_WAIT_L(0); PG8_BAR; PG8_MMA(0, 0, At, B0); PG8_MMA(0, 1, At, B1); PG8_BAR; PG8_SCHED;
;             PG8_LDA(At, 0, 1); PG8_STAGE(PG8_SB(0, 0), b2, voffB); PG8_STAGE(PG8_SB(0, 1), b2 + hB, voffB); PG8_STAGE(PG8_SA(0, 0), a2, voffA);
;             PG8_WAIT_V(8); PG8_WAIT_L(0); PG8_BAR; PG8_MMA(1, 0, At, B0); PG8_MMA(1, 1, At, B1); PG8_BAR; PG8_SCHED;
.LBB0_1153:
	s_add_u32 s8, s4, s40
	s_addc_u32 s9, s5, 0
	s_add_u32 s10, s6, 0x8000
	s_waitcnt vmcnt(0)
	v_lshl_add_u64 v[130:131], s[8:9], 0, v[0:1]
	s_addc_u32 s11, s7, 0
	s_mov_b32 s34, -2
	s_mov_b64 s[6:7], 0
	s_waitcnt lgkmcnt(0)
	s_mov_b64 s[42:43], 0xb0000
	v_add_u32_e32 v144, s90, v200
	v_add_u32_e32 v160, s15, v200
	s_add_u32 s8, s4, s6
	ds_read_b128 v[132:135], v144
	ds_read_b128 v[136:139], v144 offset:1024
	ds_read_b128 v[140:143], v144 offset:2048
	ds_read_b128 v[144:147], v144 offset:3072
	ds_read_b128 v[148:151], v160
	ds_read_b128 v[152:155], v160 offset:1024
	ds_read_b128 v[156:159], v160 offset:2048
	ds_read_b128 v[164:167], v160 offset:3072
	s_addc_u32 s9, s5, s7
	s_add_u32 s8, s8, 0x8000
	s_addc_u32 s9, s9, 0
	s_add_u32 s28, s10, s6
	s_addc_u32 s29, s11, s7
	s_cmp_eq_u32 s6, 0xa8000
	s_cselect_b32 s9, s67, s9
	s_cselect_b32 s8, s66, s8
	s_cselect_b32 vcc_hi, s87, s29
	s_cselect_b32 vcc_lo, s86, s28
	v_lshl_add_u64 v[160:161], v[130:131], 0, s[6:7]
	v_lshl_add_u64 v[196:197], v[160:161], 0, s[76:77]
	s_add_i32 m0, s0, 0xc000
	ds_read_b128 v[168:171], v201
	ds_read_b128 v[172:175], v201 offset:1024
	ds_read_b128 v[176:179], v201 offset:2048
	ds_read_b128 v[180:183], v201 offset:3072
	ds_read_b128 v[184:187], v201 offset:4096
	ds_read_b128 v[188:191], v201 offset:5120
	ds_read_b128 v[192:195], v201 offset:6144
	ds_read_b128 v[212:215], v201 offset:7168
	global_load_lds_dwordx4 v[196:197], off
	v_lshl_add_u64 v[160:161], v[160:161], 0, s[78:79]
	s_add_i32 m0, s0, 0xe000
	s_nop 0
	global_load_lds_dwordx4 v[160:161], off
	s_waitcnt vmcnt(8)
	s_waitcnt lgkmcnt(0)
	s_barrier
	s_setprio 1
	s_waitcnt lgkmcnt(0)
	v_mfma_i32_16x16x64_i8 v[122:125], v[132:135], v[168:171], 0
	v_mfma_i32_16x16x64_i8 v[126:129], v[140:143], v[168:171], 0
	v_mfma_i32_16x16x64_i8 v[114:117], v[132:135], v[176:179], 0
	v_mfma_i32_16x16x64_i8 v[118:121], v[140:143], v[176:179], 0
	v_mfma_i32_16x16x64_i8 v[106:109], v[132:135], v[184:187], 0
	v_mfma_i32_16x16x64_i8 v[110:113], v[140:143], v[184:187], 0
	v_mfma_i32_16x16x64_i8 v[98:101], v[132:135], v[192:195], 0
	v_mfma_i32_16x16x64_i8 v[102:105], v[140:143], v[192:195], 0
	v_mfma_i32_16x16x64_i8 v[122:125], v[136:139], v[172:175], v[122:125]
	v_mfma_i32_16x16x64_i8 v[126:129], v[144:147], v[172:175], v[126:129]
	v_mfma_i32_16x16x64_i8 v[114:117], v[136:139], v[180:183], v[114:117]
	v_mfma_i32_16x16x64_i8 v[118:121], v[144:147], v[180:183], v[118:121]
	v_mfma_i32_16x16x64_i8 v[106:109], v[136:139], v[188:191], v[106:109]
	v_mfma_i32_16x16x64_i8 v[110:113], v[144:147], v[188:191], v[110:113]
	v_mfma_i32_16x16x64_i8 v[98:101], v[136:139], v[212:215], v[98:101]
	v_mfma_i32_16x16x64_i8 v[102:105], v[144:147], v[212:215], v[102:105]
	s_setprio 0
	s_setprio 1
	v_mfma_i32_16x16x64_i8 v[58:61], v[148:151], v[168:171], 0
	v_mfma_i32_16x16x64_i8 v[62:65], v[156:159], v[168:171], 0
	v_mfma_i32_16x16x64_i8 v[50:53], v[148:151], v[176:179], 0
	v_mfma_i32_16x16x64_i8 v[54:57], v[156:159], v[176:179], 0
	v_mfma_i32_16x16x64_i8 v[42:45], v[148:151], v[184:187], 0
	v_mfma_i32_16x16x64_i8 v[46:49], v[156:159], v[184:187], 0
	v_mfma_i32_16x16x64_i8 v[34:37], v[148:151], v[192:195], 0
	v_mfma_i32_16x16x64_i8 v[38:41], v[156:159], v[192:195], 0
	v_mfma_i32_16x16x64_i8 v[58:61], v[152:155], v[172:175], v[58:61]
	v_mfma_i32_16x16x64_i8 v[62:65], v[164:167], v[172:175], v[62:65]
	v_mfma_i32_16x16x64_i8 v[50:53], v[152:155], v[180:183], v[50:53]
	v_mfma_i32_16x16x64_i8 v[54:57], v[164:167], v[180:183], v[54:57]
	v_mfma_i32_16x16x64_i8 v[42:45], v[152:155], v[188:191], v[42:45]
	v_mfma_i32_16x16x64_i8 v[46:49], v[164:167], v[188:191], v[46:49]
	v_mfma_i32_16x16x64_i8 v[34:37], v[152:155], v[212:215], v[34:37]
	v_mfma_i32_16x16x64_i8 v[38:41], v[164:167], v[212:215], v[38:41]
	s_setprio 0
	s_barrier
	s_mov_b32 m0, s91
	v_lshl_add_u64 v[160:161], vcc, 0, v[0:1]
	ds_read_b128 v[168:171], v201 offset:16384
	ds_read_b128 v[172:175], v201 offset:17408
	ds_read_b128 v[176:179], v201 offset:18432
	ds_read_b128 v[180:183], v201 offset:19456
	ds_read_b128 v[184:187], v201 offset:20480
	ds_read_b128 v[188:191], v201 offset:21504
	ds_read_b128 v[192:195], v201 offset:22528
	ds_read_b128 v[212:215], v201 offset:23552
	global_load_lds_dwordx4 v[160:161], off
	v_lshl_add_u64 v[196:197], v[160:161], 0, s[70:71]
	s_mov_b32 m0, s14
	s_nop 0
	global_load_lds_dwordx4 v[196:197], off
	v_lshl_add_u64 v[196:197], v[160:161], 0, s[42:43]
	s_mov_b32 m0, s26
	s_nop 0
	global_load_lds_dwordx4 v[196:197], off
	v_lshl_add_u64 v[196:197], v[160:161], 0, s[48:49]
	s_mov_b32 m0, s27
	s_nop 0
	global_load_lds_dwordx4 v[196:197], off
	v_lshl_add_u64 v[196:197], s[8:9], 0, v[0:1]
	s_mov_b32 m0, s0
	v_lshl_add_u64 v[202:203], v[196:197], 0, s[70:71]
	global_load_lds_dwordx4 v[196:197], off
	s_mov_b32 m0, s1
	s_nop 0
	global_load_lds_dwordx4 v[202:203], off
	s_waitcnt vmcnt(8)
	s_waitcnt lgkmcnt(0)
	s_barrier
; #define PG8_STAGE(bufoff, gbase, unused) do { _Pragma("unroll") for (int _i = 0; _i < 2; ++_i) \
;         __builtin_amdgcn_global_load_lds((const unsigned*)((const char*)(gbase) + voff + _i * 8192), (LAS unsigned*)(lds + (bufoff) + ldsw + _i * 8192), 16, 0, 0); } while (0)
; #define PG8_LDA(dst, b, h) do { _Pragma("unroll") for (int m = 0; m < 4; ++m) _Pragma("unroll") for (int k = 0; k < 2; ++k) dst[m][k] = *(const LAS bf16x8*)(lds + PG8_SA(b, h) + aoff + m * 2048 + (FP8 ? k * 16 : k * 1024)); } while (0)
; #define PG8_LDB(dst, b, h) do { _Pragma("unroll") for (int n = 0; n < 2; ++n) _Pragma("unroll") for (int k = 0; k < 2; ++k) dst[n][k] = *(const LAS bf16x8*)(lds + PG8_SB(b, h) + boff + n * 2048 + (FP8 ? k * 16 : k * 1024)); } while (0)
; #define PG8_WAIT_V(n) asm volatile("s_waitcnt vmcnt(" #n ")" ::: "memory")
; #define PG8_WAIT_L(n) asm volatile("s_waitcnt lgkmcnt(" #n ")" ::: "memory")
; #define PG8_BAR __builtin_amdgcn_s_barrier()
; #define PG8_SCHED __builtin_amdgcn_sched_barrier(0)
; template <class Epi, class Sched, bool ALIGN_EPI, bool SP2, int MODE  >
; __device__ __forceinline__ void gemm_phase(LAS unsigned char* lds, const Gemm g, const Sched S, const Epi E, unsigned long long& probe_acc, int epi_id, int wv) {
;     ...
;             PG8_WAIT_V(8); PG8_WAIT_L(0); PG8_BAR; PG8_MMA(1, 0, At, B0); PG8_MMA(1, 1, At, B1); PG8_BAR; PG8_SCHED;
;             PG8_LDB(B0, 1, 0); PG8_LDB(B1, 1, 1); PG8_SCHED; PG8_LDA(At, 1, 0); PG8_STAGE(PG8_SA(0, 1), a2 + hA, voffA);
;             PG8_WAIT_V(8); PG8_WAIT_L(0); PG8_BAR; PG8_MMA(0, 0, At, B0); PG8_MMA(0, 1, At, B1); PG8_BAR; PG8_SCHED;
;             PG8_LDA(At, 1, 1); PG8_STAGE(PG8_SB(1, 0), b3, voffB); PG8_STAGE(PG8_SB(1, 1), b3 + hB, voffB); PG8_STAGE(PG8_SA(1, 0), a3, voffA);
	s_setprio 1
	s_waitcnt lgkmcnt(0)
	v_mfma_i32_16x16x64_i8 v[90:93], v[132:135], v[168:171], 0
	v_mfma_i32_16x16x64_i8 v[94:97], v[140:143], v[168:171], 0
	v_mfma_i32_16x16x64_i8 v[82:85], v[132:135], v[176:179], 0
	v_mfma_i32_16x16x64_i8 v[86:89], v[140:143], v[176:179], 0
	v_mfma_i32_16x16x64_i8 v[74:77], v[132:135], v[184:187], 0
	v_mfma_i32_16x16x64_i8 v[78:81], v[140:143], v[184:187], 0
	v_mfma_i32_16x16x64_i8 v[66:69], v[132:135], v[192:195], 0
	v_mfma_i32_16x16x64_i8 v[70:73], v[140:143], v[192:195], 0
	v_mfma_i32_16x16x64_i8 v[90:93], v[136:139], v[172:175], v[90:93]
	v_mfma_i32_16x16x64_i8 v[94:97], v[144:147], v[172:175], v[94:97]
	v_mfma_i32_16x16x64_i8 v[82:85], v[136:139], v[180:183], v[82:85]
	v_mfma_i32_16x16x64_i8 v[86:89], v[144:147], v[180:183], v[86:89]
	v_mfma_i32_16x16x64_i8 v[74:77], v[136:139], v[188:191], v[74:77]
	v_mfma_i32_16x16x64_i8 v[78:81], v[144:147], v[188:191], v[78:81]
	v_mfma_i32_16x16x64_i8 v[66:69], v[136:139], v[212:215], v[66:69]
	v_mfma_i32_16x16x64_i8 v[70:73], v[144:147], v[212:215], v[70:73]
	s_setprio 0
	s_setprio 1
	v_mfma_i32_16x16x64_i8 v[26:29], v[148:151], v[168:171], 0
	v_mfma_i32_16x16x64_i8 v[30:33], v[156:159], v[168:171], 0
	v_mfma_i32_16x16x64_i8 v[18:21], v[148:151], v[176:179], 0
	v_mfma_i32_16x16x64_i8 v[22:25], v[156:159], v[176:179], 0
	v_mfma_i32_16x16x64_i8 v[10:13], v[148:151], v[184:187], 0
	v_mfma_i32_16x16x64_i8 v[14:17], v[156:159], v[184:187], 0
	v_mfma_i32_16x16x64_i8 v[2:5], v[148:151], v[192:195], 0
	v_mfma_i32_16x16x64_i8 v[6:9], v[156:159], v[192:195], 0
	v_mfma_i32_16x16x64_i8 v[26:29], v[152:155], v[172:175], v[26:29]
	v_mfma_i32_16x16x64_i8 v[30:33], v[164:167], v[172:175], v[30:33]
	v_mfma_i32_16x16x64_i8 v[18:21], v[152:155], v[180:183], v[18:21]
	v_mfma_i32_16x16x64_i8 v[22:25], v[164:167], v[180:183], v[22:25]
	v_mfma_i32_16x16x64_i8 v[10:13], v[152:155], v[188:191], v[10:13]
	v_mfma_i32_16x16x64_i8 v[14:17], v[164:167], v[188:191], v[14:17]
	v_mfma_i32_16x16x64_i8 v[2:5], v[152:155], v[212:215], v[2:5]
	v_mfma_i32_16x16x64_i8 v[6:9], v[164:167], v[212:215], v[6:9]
	s_setprio 0
	s_barrier
	v_add_u32_e32 v144, s88, v200
	v_add_u32_e32 v162, s95, v200
	ds_read_b128 v[132:135], v144
	ds_read_b128 v[136:139], v144 offset:1024
	ds_read_b128 v[140:143], v144 offset:2048
	ds_read_b128 v[144:147], v144 offset:3072
	ds_read_b128 v[148:151], v162
	ds_read_b128 v[152:155], v162 offset:1024
	ds_read_b128 v[156:159], v162 offset:2048
	ds_read_b128 v[164:167], v162 offset:3072
	s_add_u32 s8, s8, s40
	s_addc_u32 s9, s9, 0
	s_mov_b32 m0, s36
	v_lshl_add_u64 v[202:203], s[8:9], 0, v[0:1]
	ds_read_b128 v[168:171], v201 offset:32768
	ds_read_b128 v[172:175], v201 offset:33792
	ds_read_b128 v[176:179], v201 offset:34816
	ds_read_b128 v[180:183], v201 offset:35840
	ds_read_b128 v[184:187], v201 offset:36864
	ds_read_b128 v[188:191], v201 offset:37888
	ds_read_b128 v[192:195], v201 offset:38912
	ds_read_b128 v[212:215], v201 offset:39936
	global_load_lds_dwordx4 v[202:203], off
	v_lshl_add_u64 v[202:203], v[202:203], 0, s[70:71]
	s_mov_b32 m0, s37
	s_nop 0
	global_load_lds_dwordx4 v[202:203], off
	s_waitcnt vmcnt(8)
	s_waitcnt lgkmcnt(0)
	s_barrier
	s_setprio 1
	s_waitcnt lgkmcnt(0)
	v_mfma_i32_16x16x64_i8 v[122:125], v[132:135], v[168:171], v[122:125]
	v_mfma_i32_16x16x64_i8 v[126:129], v[140:143], v[168:171], v[126:129]
	v_mfma_i32_16x16x64_i8 v[114:117], v[132:135], v[176:179], v[114:117]
	v_mfma_i32_16x16x64_i8 v[118:121], v[140:143], v[176:179], v[118:121]
	v_mfma_i32_16x16x64_i8 v[106:109], v[132:135], v[184:187], v[106:109]
	v_mfma_i32_16x16x64_i8 v[110:113], v[140:143], v[184:187], v[110:113]
	v_mfma_i32_16x16x64_i8 v[98:101], v[132:135], v[192:195], v[98:101]
	v_mfma_i32_16x16x64_i8 v[102:105], v[140:143], v[192:195], v[102:105]
	v_mfma_i32_16x16x64_i8 v[122:125], v[136:139], v[172:175], v[122:125]
	v_mfma_i32_16x16x64_i8 v[126:129], v[144:147], v[172:175], v[126:129]
	v_mfma_i32_16x16x64_i8 v[114:117], v[136:139], v[180:183], v[114:117]
	v_mfma_i32_16x16x64_i8 v[118:121], v[144:147], v[180:183], v[118:121]
	v_mfma_i32_16x16x64_i8 v[106:109], v[136:139], v[188:191], v[106:109]
	v_mfma_i32_16x16x64_i8 v[110:113], v[144:147], v[188:191], v[110:113]
	v_mfma_i32_16x16x64_i8 v[98:101], v[136:139], v[212:215], v[98:101]
	v_mfma_i32_16x16x64_i8 v[102:105], v[144:147], v[212:215], v[102:105]
	s_setprio 0
	s_setprio 1
	v_mfma_i32_16x16x64_i8 v[58:61], v[148:151], v[168:171], v[58:61]
	v_mfma_i32_16x16x64_i8 v[62:65], v[156:159], v[168:171], v[62:65]
	v_mfma_i32_16x16x64_i8 v[50:53], v[148:151], v[176:179], v[50:53]
	v_mfma_i32_16x16x64_i8 v[54:57], v[156:159], v[176:179], v[54:57]
	v_mfma_i32_16x16x64_i8 v[42:45], v[148:151], v[184:187], v[42:45]
	v_mfma_i32_16x16x64_i8 v[46:49], v[156:159], v[184:187], v[46:49]
	v_mfma_i32_16x16x64_i8 v[34:37], v[148:151], v[192:195], v[34:37]
	v_mfma_i32_16x16x64_i8 v[38:41], v[156:159], v[192:195], v[38:41]
	v_mfma_i32_16x16x64_i8 v[58:61], v[152:155], v[172:175], v[58:61]
	v_mfma_i32_16x16x64_i8 v[62:65], v[164:167], v[172:175], v[62:65]
	v_mfma_i32_16x16x64_i8 v[50:53], v[152:155], v[180:183], v[50:53]
	v_mfma_i32_16x16x64_i8 v[54:57], v[164:167], v[180:183], v[54:57]
	v_mfma_i32_16x16x64_i8 v[42:45], v[152:155], v[188:191], v[42:45]
	v_mfma_i32_16x16x64_i8 v[46:49], v[164:167], v[188:191], v[46:49]
	v_mfma_i32_16x16x64_i8 v[34:37], v[152:155], v[212:215], v[34:37]
	v_mfma_i32_16x16x64_i8 v[38:41], v[164:167], v[212:215], v[38:41]
	s_setprio 0
	s_barrier
; #define PG8_STAGE(bufoff, gbase, unused) do { _Pragma("unroll") for (int _i = 0; _i < 2; ++_i) \
;         __builtin_amdgcn_global_load_lds((const unsigned*)((const char*)(gbase) + voff + _i * 8192), (LAS unsigned*)(lds + (bufoff) + ldsw + _i * 8192), 16, 0, 0); } while (0)
; #define PG8_LDA(dst, b, h) do { _Pragma("unroll") for (int m = 0; m < 4; ++m) _Pragma("unroll") for (int k = 0; k < 2; ++k) dst[m][k] = *(const LAS bf16x8*)(lds + PG8_SA(b, h) + aoff + m * 2048 + (FP8 ? k * 16 : k * 1024)); } while (0)
; #define PG8_WAIT_V(n) asm volatile("s_waitcnt vmcnt(" #n ")" ::: "memory")
; #define PG8_WAIT_L(n) asm volatile("s_waitcnt lgkmcnt(" #n ")" ::: "memory")
; #define PG8_BAR __builtin_amdgcn_s_barrier()
; #define PG8_SCHED __builtin_amdgcn_sched_barrier(0)
; template <class Epi, class Sched, bool ALIGN_EPI, bool SP2, int MODE  >
; __device__ __forceinline__ void gemm_phase(LAS unsigned char* lds, const Gemm g, const Sched S, const Epi E, unsigned long long& probe_acc, int epi_id, int wv) {
;     ...
;             PG8_LDA(At, 1, 1); PG8_STAGE(PG8_SB(1, 0), b3, voffB); PG8_STAGE(PG8_SB(1, 1), b3 + hB, voffB); PG8_STAGE(PG8_SA(1, 0), a3, voffA);
;             PG8_WAIT_V(8); PG8_WAIT_L(0); PG8_BAR; PG8_MMA(1, 0, At, B0); PG8_MMA(1, 1, At, B1); PG8_BAR; PG8_SCHED;
	s_mov_b32 m0, s89
	v_lshl_add_u64 v[202:203], v[160:161], 0, s[76:77]
	ds_read_b128 v[168:171], v201 offset:49152
	ds_read_b128 v[172:175], v201 offset:50176
	ds_read_b128 v[176:179], v201 offset:51200
	ds_read_b128 v[180:183], v201 offset:52224
	ds_read_b128 v[184:187], v201 offset:53248
	ds_read_b128 v[188:191], v201 offset:54272
	ds_read_b128 v[192:195], v201 offset:55296
	ds_read_b128 v[212:215], v201 offset:56320
	global_load_lds_dwordx4 v[202:203], off
	v_lshl_add_u64 v[202:203], v[160:161], 0, s[78:79]
	s_mov_b32 m0, s92
	s_nop 0
	global_load_lds_dwordx4 v[202:203], off
	v_lshl_add_u64 v[202:203], v[160:161], 0, s[44:45]
	s_mov_b32 m0, s84
	v_lshl_add_u64 v[160:161], v[160:161], 0, s[56:57]
	global_load_lds_dwordx4 v[202:203], off
	s_mov_b32 m0, s12
	s_nop 0
	global_load_lds_dwordx4 v[160:161], off
	v_lshl_add_u64 v[160:161], v[196:197], 0, s[76:77]
	s_mov_b32 m0, s93
	s_nop 0
	global_load_lds_dwordx4 v[160:161], off
	v_lshl_add_u64 v[160:161], v[196:197], 0, s[78:79]
	s_mov_b32 m0, s94
	s_nop 0
	global_load_lds_dwordx4 v[160:161], off
	s_waitcnt vmcnt(8)
	s_waitcnt lgkmcnt(0)
	s_barrier
	s_setprio 1
	s_waitcnt lgkmcnt(0)
	v_mfma_i32_16x16x64_i8 v[90:93], v[132:135], v[168:171], v[90:93]
	v_mfma_i32_16x16x64_i8 v[94:97], v[140:143], v[168:171], v[94:97]
	v_mfma_i32_16x16x64_i8 v[82:85], v[132:135], v[176:179], v[82:85]
	v_mfma_i32_16x16x64_i8 v[86:89], v[140:143], v[176:179], v[86:89]
	v_mfma_i32_16x16x64_i8 v[74:77], v[132:135], v[184:187], v[74:77]
	v_mfma_i32_16x16x64_i8 v[78:81], v[140:143], v[184:187], v[78:81]
	v_mfma_i32_16x16x64_i8 v[66:69], v[132:135], v[192:195], v[66:69]
	v_mfma_i32_16x16x64_i8 v[70:73], v[140:143], v[192:195], v[70:73]
	v_mfma_i32_16x16x64_i8 v[90:93], v[136:139], v[172:175], v[90:93]
	v_mfma_i32_16x16x64_i8 v[94:97], v[144:147], v[172:175], v[94:97]
	v_mfma_i32_16x16x64_i8 v[82:85], v[136:139], v[180:183], v[82:85]
	v_mfma_i32_16x16x64_i8 v[86:89], v[144:147], v[180:183], v[86:89]
	v_mfma_i32_16x16x64_i8 v[74:77], v[136:139], v[188:191], v[74:77]
	v_mfma_i32_16x16x64_i8 v[78:81], v[144:147], v[188:191], v[78:81]
	v_mfma_i32_16x16x64_i8 v[66:69], v[136:139], v[212:215], v[66:69]
	v_mfma_i32_16x16x64_i8 v[70:73], v[144:147], v[212:215], v[70:73]
	s_setprio 0
	s_setprio 1
	v_mfma_i32_16x16x64_i8 v[26:29], v[148:151], v[168:171], v[26:29]
	v_mfma_i32_16x16x64_i8 v[30:33], v[156:159], v[168:171], v[30:33]
	v_mfma_i32_16x16x64_i8 v[18:21], v[148:151], v[176:179], v[18:21]
	v_mfma_i32_16x16x64_i8 v[22:25], v[156:159], v[176:179], v[22:25]
	v_mfma_i32_16x16x64_i8 v[10:13], v[148:151], v[184:187], v[10:13]
	v_mfma_i32_16x16x64_i8 v[14:17], v[156:159], v[184:187], v[14:17]
	v_mfma_i32_16x16x64_i8 v[2:5], v[148:151], v[192:195], v[2:5]
	v_mfma_i32_16x16x64_i8 v[6:9], v[156:159], v[192:195], v[6:9]
	v_mfma_i32_16x16x64_i8 v[26:29], v[152:155], v[172:175], v[26:29]
	v_mfma_i32_16x16x64_i8 v[30:33], v[164:167], v[172:175], v[30:33]
	v_mfma_i32_16x16x64_i8 v[18:21], v[152:155], v[180:183], v[18:21]
	v_mfma_i32_16x16x64_i8 v[22:25], v[164:167], v[180:183], v[22:25]
	v_mfma_i32_16x16x64_i8 v[10:13], v[152:155], v[188:191], v[10:13]
	v_mfma_i32_16x16x64_i8 v[14:17], v[164:167], v[188:191], v[14:17]
	v_mfma_i32_16x16x64_i8 v[2:5], v[152:155], v[212:215], v[2:5]
	v_mfma_i32_16x16x64_i8 v[6:9], v[164:167], v[212:215], v[6:9]
	s_setprio 0
	s_barrier
	s_add_i32 s34, s34, 2
	s_add_u32 s6, s6, 0x8000
	s_addc_u32 s7, s7, 0
	s_cmp_gt_u32 s34, 41
